# peel first K-loop iteration per tile with srcC=0 MFMAs instead of 128 v_mov accumulator zeroing (all 4 GEMM loops)
# speedup vs baseline: 1.0038x; 1.0038x over previous
; #define PG8_STAGE(bufoff, gbase, voff) do { _Pragma("unroll") for (int _i = 0; _i < 2; ++_i) \
;         __builtin_amdgcn_global_load_lds((const unsigned*)((const char*)(gbase) + (voff)[_i]), (PG8_LAS unsigned*)(lds + (bufoff) + ldsw + _i * 8192), 16, 0, 0); } while (0)
; #define PG8_LDA(dst, b, h) do { _Pragma("unroll") for (int m = 0; m < 4; ++m) _Pragma("unroll") for (int k = 0; k < 2; ++k) dst[m][k] = *(const PG8_LAS bf16x8*)(lds + PG8_SA(b, h) + aoff + m * 2048 + k * 1024); } while (0)
; #define PG8_LDB(dst, b, h) do { _Pragma("unroll") for (int n = 0; n < 2; ++n) _Pragma("unroll") for (int k = 0; k < 2; ++k) dst[n][k] = *(const PG8_LAS bf16x8*)(lds + PG8_SB(b, h) + boff + n * 2048 + k * 1024); } while (0)
; #define PG8_WAIT_V(n) asm volatile("s_waitcnt vmcnt(" #n ")" ::: "memory")
; #define PG8_WAIT_L(n) asm volatile("s_waitcnt lgkmcnt(" #n ")" ::: "memory")
; #define PG8_BAR __builtin_amdgcn_s_barrier()
; template <class Epi, class Sched, bool ALIGN_EPI = false, bool SP2 = false>
; __device__ __forceinline__ void gemm_phase(PG8_LAS unsigned char* lds, const Gemm g, const Sched& S, const Epi& E) {
;     ...
;         for (int t = 0; t < nt; t += 2) {
;             const bool last = (t == nt - 2);
;             const char* a1 = cA + (size_t)(t + 1) * kstep;
;             const char* a2 = last ? nA : cA + (size_t)(t + 2) * kstep; const char* b2 = last ? nB : cB + (size_t)(t + 2) * kstep;
;             const char* a3 = a2 + kstep; const char* b3 = b2 + kstep;
;             if (last && has_next) S.a_ready(nxt);
;             if constexpr (SP2) {
;             PG8_LDB(B0, 0, 0); PG8_LDB(B1, 0, 1); PG8_SCHED; PG8_LDA(At, 0, 0); PG8_STAGE(PG8_SA(1, 1), a1 + hstep, voffA);
;             PG8_WAIT_V(8); PG8_WAIT_L(0); PG8_BAR; PG8_MMA(0, 0, At, B0); PG8_MMA(0, 1, At, B1); PG8_BAR; PG8_SCHED;
;             PG8_LDA(At, 0, 1); PG8_STAGE(PG8_SB(0, 0), b2, voffB); PG8_STAGE(PG8_SB(0, 1), b2 + hstep, voffB); PG8_STAGE(PG8_SA(0, 0), a2, voffA);
;             PG8_WAIT_V(8); PG8_WAIT_L(0); PG8_BAR; PG8_MMA(1, 0, At, B0); PG8_MMA(1, 1, At, B1); PG8_BAR; PG8_SCHED;
;     ...
; #pragma unroll
;         for (int a = 0; a < 2; ++a)
; #pragma unroll
;             for (int b = 0; b < 2; ++b)
; #pragma unroll
;                 for (int m = 0; m < 4; ++m)
; #pragma unroll
;                     for (int n = 0; n < 2; ++n) acc[a][b][m][n] = (f32x4){0.f, 0.f, 0.f, 0.f};
.Lz_enter_339:
	s_add_u32 s16, s16, 0x80
	s_addc_u32 s17, s17, 0
	s_add_u32 s33, s20, 0x100
	s_addc_u32 s39, s21, 0
	s_mov_b32 s20, 0
	s_add_i32 s44, s20, 2
	s_add_u32 s45, s16, 0x80
	s_addc_u32 s21, s17, 0
	s_cmp_eq_u32 s70, s20
	s_cselect_b32 s21, s7, s21
	s_cselect_b32 s20, s6, s45
	s_cselect_b32 s47, s57, s39
	s_cselect_b32 s46, s56, s33
	ds_read_b128 v[82:85], v167
	ds_read_b128 v[86:89], v167 offset:1024
	ds_read_b128 v[138:141], v167 offset:2048
	ds_read_b128 v[142:145], v167 offset:3072
	ds_read_b128 v[158:161], v167 offset:16384
	ds_read_b128 v[162:165], v167 offset:17408
	ds_read_b128 v[170:173], v167 offset:18432
	ds_read_b128 v[174:177], v167 offset:19456
	s_add_i32 m0, s63, 0xc000
	ds_read_b128 v[178:181], v169
	ds_read_b128 v[182:185], v169 offset:1024
	ds_read_b128 v[186:189], v169 offset:2048
	ds_read_b128 v[190:193], v169 offset:3072
	ds_read_b128 v[194:197], v169 offset:4096
	ds_read_b128 v[198:201], v169 offset:5120
	ds_read_b128 v[202:205], v169 offset:6144
	global_load_lds_dwordx4 v154, s[16:17]
	s_add_i32 m0, s63, 0xe000
	ds_read_b128 v[206:209], v169 offset:7168
	global_load_lds_dwordx4 v156, s[16:17]
	s_waitcnt vmcnt(8)
	s_waitcnt lgkmcnt(0)
	s_barrier
	s_setprio 1
	v_mfma_f32_16x16x32_bf16 v[134:137], v[82:85], v[178:181], 0
	v_mfma_f32_16x16x32_bf16 v[130:133], v[138:141], v[178:181], 0
	v_mfma_f32_16x16x32_bf16 v[126:129], v[82:85], v[186:189], 0
	v_mfma_f32_16x16x32_bf16 v[122:125], v[138:141], v[186:189], 0
	v_mfma_f32_16x16x32_bf16 v[118:121], v[82:85], v[194:197], 0
	v_mfma_f32_16x16x32_bf16 v[114:117], v[138:141], v[194:197], 0
	v_mfma_f32_16x16x32_bf16 v[110:113], v[82:85], v[202:205], 0
	v_mfma_f32_16x16x32_bf16 v[106:109], v[138:141], v[202:205], 0
	v_mfma_f32_16x16x32_bf16 v[134:137], v[86:89], v[182:185], v[134:137]
	v_mfma_f32_16x16x32_bf16 v[130:133], v[142:145], v[182:185], v[130:133]
	v_mfma_f32_16x16x32_bf16 v[126:129], v[86:89], v[190:193], v[126:129]
	v_mfma_f32_16x16x32_bf16 v[122:125], v[142:145], v[190:193], v[122:125]
	v_mfma_f32_16x16x32_bf16 v[118:121], v[86:89], v[198:201], v[118:121]
	v_mfma_f32_16x16x32_bf16 v[114:117], v[142:145], v[198:201], v[114:117]
	v_mfma_f32_16x16x32_bf16 v[110:113], v[86:89], v[206:209], v[110:113]
	v_mfma_f32_16x16x32_bf16 v[106:109], v[142:145], v[206:209], v[106:109]
	v_mfma_f32_16x16x32_bf16 v[62:65], v[158:161], v[178:181], 0
	v_mfma_f32_16x16x32_bf16 v[58:61], v[170:173], v[178:181], 0
	v_mfma_f32_16x16x32_bf16 v[54:57], v[158:161], v[186:189], 0
	v_mfma_f32_16x16x32_bf16 v[50:53], v[170:173], v[186:189], 0
	v_mfma_f32_16x16x32_bf16 v[46:49], v[158:161], v[194:197], 0
	v_mfma_f32_16x16x32_bf16 v[42:45], v[170:173], v[194:197], 0
	v_mfma_f32_16x16x32_bf16 v[38:41], v[158:161], v[202:205], 0
	v_mfma_f32_16x16x32_bf16 v[34:37], v[170:173], v[202:205], 0
	v_mfma_f32_16x16x32_bf16 v[62:65], v[162:165], v[182:185], v[62:65]
	v_mfma_f32_16x16x32_bf16 v[58:61], v[174:177], v[182:185], v[58:61]
	v_mfma_f32_16x16x32_bf16 v[54:57], v[162:165], v[190:193], v[54:57]
	v_mfma_f32_16x16x32_bf16 v[50:53], v[174:177], v[190:193], v[50:53]
	v_mfma_f32_16x16x32_bf16 v[46:49], v[162:165], v[198:201], v[46:49]
	v_mfma_f32_16x16x32_bf16 v[42:45], v[174:177], v[198:201], v[42:45]
	v_mfma_f32_16x16x32_bf16 v[38:41], v[162:165], v[206:209], v[38:41]
	v_mfma_f32_16x16x32_bf16 v[34:37], v[174:177], v[206:209], v[34:37]
	s_setprio 0
	s_barrier
	v_lshl_add_u64 v[210:211], s[46:47], 0, v[148:149]
	s_add_i32 m0, s62, 0x10000
	ds_read_b128 v[178:181], v169 offset:16384
	ds_read_b128 v[182:185], v169 offset:17408
	ds_read_b128 v[186:189], v169 offset:18432
	ds_read_b128 v[190:193], v169 offset:19456
	ds_read_b128 v[194:197], v169 offset:20480
	ds_read_b128 v[198:201], v169 offset:21504
	ds_read_b128 v[202:205], v169 offset:22528
	ds_read_b128 v[206:209], v169 offset:23552
	global_load_lds_dwordx4 v[210:211], off
	s_add_i32 m0, s62, 0x12000
	v_lshl_add_u64 v[212:213], s[46:47], 0, v[152:153]
	s_add_u32 s46, s46, s10
	s_addc_u32 s47, s47, s11
	global_load_lds_dwordx4 v[212:213], off
	v_lshl_add_u64 v[214:215], s[46:47], 0, v[148:149]
	s_add_i32 m0, s62, 0x14000
	v_lshl_add_u64 v[218:219], s[46:47], 0, v[152:153]
	global_load_lds_dwordx4 v[214:215], off
	s_add_i32 m0, s62, 0x16000
	v_lshl_add_u64 v[220:221], s[20:21], 0, v[146:147]
	global_load_lds_dwordx4 v[218:219], off
	s_mov_b32 m0, s63
	v_lshl_add_u64 v[222:223], s[20:21], 0, v[150:151]
	global_load_lds_dwordx4 v[220:221], off
	s_mov_b32 m0, s64
	s_nop 0
	global_load_lds_dwordx4 v[222:223], off
	s_waitcnt vmcnt(8)
	s_waitcnt lgkmcnt(0)
	s_barrier
	s_setprio 1
	v_mfma_f32_16x16x32_bf16 v[102:105], v[82:85], v[178:181], 0
	v_mfma_f32_16x16x32_bf16 v[98:101], v[138:141], v[178:181], 0
	v_mfma_f32_16x16x32_bf16 v[94:97], v[82:85], v[186:189], 0
	v_mfma_f32_16x16x32_bf16 v[90:93], v[138:141], v[186:189], 0
	v_mfma_f32_16x16x32_bf16 v[78:81], v[82:85], v[194:197], 0
	v_mfma_f32_16x16x32_bf16 v[74:77], v[138:141], v[194:197], 0
	v_mfma_f32_16x16x32_bf16 v[70:73], v[82:85], v[202:205], 0
	v_mfma_f32_16x16x32_bf16 v[66:69], v[138:141], v[202:205], 0
	v_mfma_f32_16x16x32_bf16 v[102:105], v[86:89], v[182:185], v[102:105]
	v_mfma_f32_16x16x32_bf16 v[98:101], v[142:145], v[182:185], v[98:101]
	v_mfma_f32_16x16x32_bf16 v[94:97], v[86:89], v[190:193], v[94:97]
	v_mfma_f32_16x16x32_bf16 v[90:93], v[142:145], v[190:193], v[90:93]
	v_mfma_f32_16x16x32_bf16 v[78:81], v[86:89], v[198:201], v[78:81]
	v_mfma_f32_16x16x32_bf16 v[74:77], v[142:145], v[198:201], v[74:77]
	v_mfma_f32_16x16x32_bf16 v[70:73], v[86:89], v[206:209], v[70:73]
	v_mfma_f32_16x16x32_bf16 v[66:69], v[142:145], v[206:209], v[66:69]
	v_mfma_f32_16x16x32_bf16 v[30:33], v[158:161], v[178:181], 0
	v_mfma_f32_16x16x32_bf16 v[26:29], v[170:173], v[178:181], 0
	v_mfma_f32_16x16x32_bf16 v[22:25], v[158:161], v[186:189], 0
	v_mfma_f32_16x16x32_bf16 v[18:21], v[170:173], v[186:189], 0
	v_mfma_f32_16x16x32_bf16 v[14:17], v[158:161], v[194:197], 0
	v_mfma_f32_16x16x32_bf16 v[10:13], v[170:173], v[194:197], 0
	v_mfma_f32_16x16x32_bf16 v[6:9], v[158:161], v[202:205], 0
	v_mfma_f32_16x16x32_bf16 v[2:5], v[170:173], v[202:205], 0
	v_mfma_f32_16x16x32_bf16 v[30:33], v[162:165], v[182:185], v[30:33]
	v_mfma_f32_16x16x32_bf16 v[26:29], v[174:177], v[182:185], v[26:29]
	v_mfma_f32_16x16x32_bf16 v[22:25], v[162:165], v[190:193], v[22:25]
	v_mfma_f32_16x16x32_bf16 v[18:21], v[174:177], v[190:193], v[18:21]
	v_mfma_f32_16x16x32_bf16 v[14:17], v[162:165], v[198:201], v[14:17]
	v_mfma_f32_16x16x32_bf16 v[10:13], v[174:177], v[198:201], v[10:13]
	v_mfma_f32_16x16x32_bf16 v[6:9], v[162:165], v[206:209], v[6:9]
	v_mfma_f32_16x16x32_bf16 v[2:5], v[174:177], v[206:209], v[2:5]
	s_setprio 0
	s_barrier
; #define PG8_STAGE(bufoff, gbase, voff) do { _Pragma("unroll") for (int _i = 0; _i < 2; ++_i) \
;         __builtin_amdgcn_global_load_lds((const unsigned*)((const char*)(gbase) + (voff)[_i]), (PG8_LAS unsigned*)(lds + (bufoff) + ldsw + _i * 8192), 16, 0, 0); } while (0)
; #define PG8_LDA(dst, b, h) do { _Pragma("unroll") for (int m = 0; m < 4; ++m) _Pragma("unroll") for (int k = 0; k < 2; ++k) dst[m][k] = *(const PG8_LAS bf16x8*)(lds + PG8_SA(b, h) + aoff + m * 2048 + k * 1024); } while (0)
; #define PG8_LDB(dst, b, h) do { _Pragma("unroll") for (int n = 0; n < 2; ++n) _Pragma("unroll") for (int k = 0; k < 2; ++k) dst[n][k] = *(const PG8_LAS bf16x8*)(lds + PG8_SB(b, h) + boff + n * 2048 + k * 1024); } while (0)
; #define PG8_MMA(ai, bj, At, Bt) do { __builtin_amdgcn_s_setprio(1); _Pragma("unroll") for (int m = 0; m < 4; ++m) _Pragma("unroll") for (int n = 0; n < 2; ++n) _Pragma("unroll") for (int k = 0; k < 2; ++k) \
;         acc[ai][bj][m][n] = __builtin_amdgcn_mfma_f32_16x16x32_bf16(Bt[n][k], At[m][k], acc[ai][bj][m][n], 0, 0, 0); __builtin_amdgcn_s_setprio(0); } while (0)
; #define PG8_WAIT_V(n) asm volatile("s_waitcnt vmcnt(" #n ")" ::: "memory")
; #define PG8_WAIT_L(n) asm volatile("s_waitcnt lgkmcnt(" #n ")" ::: "memory")
; #define PG8_BAR __builtin_amdgcn_s_barrier()
; #define PG8_SCHED __builtin_amdgcn_sched_barrier(0)
; template <class Epi, class Sched, bool ALIGN_EPI = false, bool SP2 = false>
; __device__ __forceinline__ void gemm_phase(PG8_LAS unsigned char* lds, const Gemm g, const Sched& S, const Epi& E) {
;     ...
;             PG8_LDB(B0, 1, 0); PG8_LDB(B1, 1, 1); PG8_SCHED; PG8_LDA(At, 1, 0); PG8_STAGE(PG8_SA(0, 1), a2 + hstep, voffA);
;             PG8_WAIT_V(8); PG8_WAIT_L(0); PG8_BAR; PG8_MMA(0, 0, At, B0); PG8_MMA(0, 1, At, B1); PG8_BAR; PG8_SCHED;
;             PG8_LDA(At, 1, 1); PG8_STAGE(PG8_SB(1, 0), b3, voffB); PG8_STAGE(PG8_SB(1, 1), b3 + hstep, voffB); PG8_STAGE(PG8_SA(1, 0), a3, voffA);
;             PG8_WAIT_V(8); PG8_WAIT_L(0); PG8_BAR; PG8_MMA(1, 0, At, B0); PG8_MMA(1, 1, At, B1); PG8_BAR; PG8_SCHED;
	ds_read_b128 v[82:85], v167 offset:32768
	ds_read_b128 v[86:89], v167 offset:33792
	ds_read_b128 v[138:141], v167 offset:34816
	ds_read_b128 v[142:145], v167 offset:35840
	ds_read_b128 v[158:161], v167 offset:49152
	ds_read_b128 v[162:165], v167 offset:50176
	ds_read_b128 v[170:173], v167 offset:51200
	ds_read_b128 v[174:177], v167 offset:52224
	s_mov_b32 m0, s65
	ds_read_b128 v[178:181], v169 offset:32768
	ds_read_b128 v[182:185], v169 offset:33792
	ds_read_b128 v[186:189], v169 offset:34816
	ds_read_b128 v[190:193], v169 offset:35840
	ds_read_b128 v[194:197], v169 offset:36864
	ds_read_b128 v[198:201], v169 offset:37888
	ds_read_b128 v[202:205], v169 offset:38912
	global_load_lds_dwordx4 v154, s[20:21]
	s_mov_b32 m0, s66
	ds_read_b128 v[206:209], v169 offset:39936
	global_load_lds_dwordx4 v156, s[20:21]
	s_waitcnt vmcnt(8)
	s_waitcnt lgkmcnt(0)
	s_barrier
	s_setprio 1
	v_mfma_f32_16x16x32_bf16 v[134:137], v[82:85], v[178:181], v[134:137]
	v_mfma_f32_16x16x32_bf16 v[130:133], v[138:141], v[178:181], v[130:133]
	v_mfma_f32_16x16x32_bf16 v[126:129], v[82:85], v[186:189], v[126:129]
	v_mfma_f32_16x16x32_bf16 v[122:125], v[138:141], v[186:189], v[122:125]
	v_mfma_f32_16x16x32_bf16 v[118:121], v[82:85], v[194:197], v[118:121]
	v_mfma_f32_16x16x32_bf16 v[114:117], v[138:141], v[194:197], v[114:117]
	v_mfma_f32_16x16x32_bf16 v[110:113], v[82:85], v[202:205], v[110:113]
	v_mfma_f32_16x16x32_bf16 v[106:109], v[138:141], v[202:205], v[106:109]
	v_mfma_f32_16x16x32_bf16 v[134:137], v[86:89], v[182:185], v[134:137]
	v_mfma_f32_16x16x32_bf16 v[130:133], v[142:145], v[182:185], v[130:133]
	v_mfma_f32_16x16x32_bf16 v[126:129], v[86:89], v[190:193], v[126:129]
	v_mfma_f32_16x16x32_bf16 v[122:125], v[142:145], v[190:193], v[122:125]
	v_mfma_f32_16x16x32_bf16 v[118:121], v[86:89], v[198:201], v[118:121]
	v_mfma_f32_16x16x32_bf16 v[114:117], v[142:145], v[198:201], v[114:117]
	v_mfma_f32_16x16x32_bf16 v[110:113], v[86:89], v[206:209], v[110:113]
	v_mfma_f32_16x16x32_bf16 v[106:109], v[142:145], v[206:209], v[106:109]
	v_mfma_f32_16x16x32_bf16 v[62:65], v[158:161], v[178:181], v[62:65]
	v_mfma_f32_16x16x32_bf16 v[58:61], v[170:173], v[178:181], v[58:61]
	v_mfma_f32_16x16x32_bf16 v[54:57], v[158:161], v[186:189], v[54:57]
	v_mfma_f32_16x16x32_bf16 v[50:53], v[170:173], v[186:189], v[50:53]
	v_mfma_f32_16x16x32_bf16 v[46:49], v[158:161], v[194:197], v[46:49]
	v_mfma_f32_16x16x32_bf16 v[42:45], v[170:173], v[194:197], v[42:45]
	v_mfma_f32_16x16x32_bf16 v[38:41], v[158:161], v[202:205], v[38:41]
	v_mfma_f32_16x16x32_bf16 v[34:37], v[170:173], v[202:205], v[34:37]
	v_mfma_f32_16x16x32_bf16 v[62:65], v[162:165], v[182:185], v[62:65]
	v_mfma_f32_16x16x32_bf16 v[58:61], v[174:177], v[182:185], v[58:61]
	v_mfma_f32_16x16x32_bf16 v[54:57], v[162:165], v[190:193], v[54:57]
	v_mfma_f32_16x16x32_bf16 v[50:53], v[174:177], v[190:193], v[50:53]
	v_mfma_f32_16x16x32_bf16 v[46:49], v[162:165], v[198:201], v[46:49]
	v_mfma_f32_16x16x32_bf16 v[42:45], v[174:177], v[198:201], v[42:45]
	v_mfma_f32_16x16x32_bf16 v[38:41], v[162:165], v[206:209], v[38:41]
	v_mfma_f32_16x16x32_bf16 v[34:37], v[174:177], v[206:209], v[34:37]
	s_setprio 0
	s_barrier
	s_add_i32 m0, s62, 0x17f80
	ds_read_b128 v[178:181], v169 offset:49152
	ds_read_b128 v[182:185], v169 offset:50176
	ds_read_b128 v[186:189], v169 offset:51200
	global_load_lds_dwordx4 v[210:211], off offset:128
	s_add_i32 m0, s62, 0x19f80
	ds_read_b128 v[190:193], v169 offset:52224
	global_load_lds_dwordx4 v[212:213], off offset:128
	s_add_i32 m0, s62, 0x1bf80
	ds_read_b128 v[194:197], v169 offset:53248
	global_load_lds_dwordx4 v[214:215], off offset:128
	s_add_i32 m0, s62, 0x1df80
	ds_read_b128 v[198:201], v169 offset:54272
	global_load_lds_dwordx4 v[218:219], off offset:128
	s_sub_i32 m0, s68, 0x80
	ds_read_b128 v[202:205], v169 offset:55296
	global_load_lds_dwordx4 v[220:221], off offset:128
	s_sub_i32 m0, s69, 0x80
	ds_read_b128 v[206:209], v169 offset:56320
	global_load_lds_dwordx4 v[222:223], off offset:128
	s_waitcnt vmcnt(8)
	s_waitcnt lgkmcnt(0)
	s_barrier
	s_setprio 1
	v_mfma_f32_16x16x32_bf16 v[102:105], v[82:85], v[178:181], v[102:105]
	v_mfma_f32_16x16x32_bf16 v[98:101], v[138:141], v[178:181], v[98:101]
	v_mfma_f32_16x16x32_bf16 v[94:97], v[82:85], v[186:189], v[94:97]
	v_mfma_f32_16x16x32_bf16 v[90:93], v[138:141], v[186:189], v[90:93]
	v_mfma_f32_16x16x32_bf16 v[78:81], v[82:85], v[194:197], v[78:81]
	v_mfma_f32_16x16x32_bf16 v[74:77], v[138:141], v[194:197], v[74:77]
	v_mfma_f32_16x16x32_bf16 v[70:73], v[82:85], v[202:205], v[70:73]
	v_mfma_f32_16x16x32_bf16 v[66:69], v[138:141], v[202:205], v[66:69]
	v_mfma_f32_16x16x32_bf16 v[102:105], v[86:89], v[182:185], v[102:105]
	v_mfma_f32_16x16x32_bf16 v[98:101], v[142:145], v[182:185], v[98:101]
	v_mfma_f32_16x16x32_bf16 v[94:97], v[86:89], v[190:193], v[94:97]
	v_mfma_f32_16x16x32_bf16 v[90:93], v[142:145], v[190:193], v[90:93]
	v_mfma_f32_16x16x32_bf16 v[78:81], v[86:89], v[198:201], v[78:81]
	v_mfma_f32_16x16x32_bf16 v[74:77], v[142:145], v[198:201], v[74:77]
	v_mfma_f32_16x16x32_bf16 v[70:73], v[86:89], v[206:209], v[70:73]
	v_mfma_f32_16x16x32_bf16 v[66:69], v[142:145], v[206:209], v[66:69]
	v_mfma_f32_16x16x32_bf16 v[30:33], v[158:161], v[178:181], v[30:33]
	v_mfma_f32_16x16x32_bf16 v[26:29], v[170:173], v[178:181], v[26:29]
	v_mfma_f32_16x16x32_bf16 v[22:25], v[158:161], v[186:189], v[22:25]
	v_mfma_f32_16x16x32_bf16 v[18:21], v[170:173], v[186:189], v[18:21]
	v_mfma_f32_16x16x32_bf16 v[14:17], v[158:161], v[194:197], v[14:17]
	v_mfma_f32_16x16x32_bf16 v[10:13], v[170:173], v[194:197], v[10:13]
	v_mfma_f32_16x16x32_bf16 v[6:9], v[158:161], v[202:205], v[6:9]
	v_mfma_f32_16x16x32_bf16 v[2:5], v[170:173], v[202:205], v[2:5]
	v_mfma_f32_16x16x32_bf16 v[30:33], v[162:165], v[182:185], v[30:33]
	v_mfma_f32_16x16x32_bf16 v[26:29], v[174:177], v[182:185], v[26:29]
	v_mfma_f32_16x16x32_bf16 v[22:25], v[162:165], v[190:193], v[22:25]
	v_mfma_f32_16x16x32_bf16 v[18:21], v[174:177], v[190:193], v[18:21]
	v_mfma_f32_16x16x32_bf16 v[14:17], v[162:165], v[198:201], v[14:17]
	v_mfma_f32_16x16x32_bf16 v[10:13], v[174:177], v[198:201], v[10:13]
	v_mfma_f32_16x16x32_bf16 v[6:9], v[162:165], v[206:209], v[6:9]
	v_mfma_f32_16x16x32_bf16 v[2:5], v[174:177], v[206:209], v[2:5]
	s_setprio 0
	s_barrier
	s_add_u32 s16, s16, 0x100
	s_addc_u32 s17, s17, 0
	s_add_u32 s33, s33, 0x100
	s_addc_u32 s39, s39, 0
	s_cmp_ge_i32 s44, s67
	s_mov_b32 s20, s44
	s_cbranch_scc1 .Lpz_exit_341

; #define PG8_BAR __builtin_amdgcn_s_barrier()
; template <class Epi, class Sched, bool ALIGN_EPI = false, bool SP2 = false>
; __device__ __forceinline__ void gemm_phase(PG8_LAS unsigned char* lds, const Gemm g, const Sched& S, const Epi& E) {
;     ...
;         if constexpr (ALIGN_EPI) { if (wr == 0) PG8_BAR; }
;         if constexpr (!Epi::AFTER_DRAIN) { E(acc, cur, wr, wc, fr, fq); S.done(cur); }
.Lpz_exit_341:
	s_movk_i32 s39, 0x5000

; #define PG8_STAGE(bufoff, gbase, voff) do { _Pragma("unroll") for (int _i = 0; _i < 2; ++_i) \
;         __builtin_amdgcn_global_load_lds((const unsigned*)((const char*)(gbase) + (voff)[_i]), (PG8_LAS unsigned*)(lds + (bufoff) + ldsw + _i * 8192), 16, 0, 0); } while (0)
; #define PG8_LDA(dst, b, h) do { _Pragma("unroll") for (int m = 0; m < 4; ++m) _Pragma("unroll") for (int k = 0; k < 2; ++k) dst[m][k] = *(const PG8_LAS bf16x8*)(lds + PG8_SA(b, h) + aoff + m * 2048 + k * 1024); } while (0)
; #define PG8_LDB(dst, b, h) do { _Pragma("unroll") for (int n = 0; n < 2; ++n) _Pragma("unroll") for (int k = 0; k < 2; ++k) dst[n][k] = *(const PG8_LAS bf16x8*)(lds + PG8_SB(b, h) + boff + n * 2048 + k * 1024); } while (0)
; #define PG8_WAIT_V(n) asm volatile("s_waitcnt vmcnt(" #n ")" ::: "memory")
; #define PG8_WAIT_L(n) asm volatile("s_waitcnt lgkmcnt(" #n ")" ::: "memory")
; #define PG8_BAR __builtin_amdgcn_s_barrier()
; template <class Epi, class Sched, bool ALIGN_EPI = false, bool SP2 = false>
; __device__ __forceinline__ void gemm_phase(PG8_LAS unsigned char* lds, const Gemm g, const Sched& S, const Epi& E) {
;     ...
;         for (int t = 0; t < nt; t += 2) {
;             const bool last = (t == nt - 2);
;             const char* a1 = cA + (size_t)(t + 1) * kstep;
;             const char* a2 = last ? nA : cA + (size_t)(t + 2) * kstep; const char* b2 = last ? nB : cB + (size_t)(t + 2) * kstep;
;             const char* a3 = a2 + kstep; const char* b3 = b2 + kstep;
;             if (last && has_next) S.a_ready(nxt);
;             if constexpr (SP2) {
;             PG8_LDB(B0, 0, 0); PG8_LDB(B1, 0, 1); PG8_SCHED; PG8_LDA(At, 0, 0); PG8_STAGE(PG8_SA(1, 1), a1 + hstep, voffA);
;             PG8_WAIT_V(8); PG8_WAIT_L(0); PG8_BAR; PG8_MMA(0, 0, At, B0); PG8_MMA(0, 1, At, B1); PG8_BAR; PG8_SCHED;
;             PG8_LDA(At, 0, 1); PG8_STAGE(PG8_SB(0, 0), b2, voffB); PG8_STAGE(PG8_SB(0, 1), b2 + hstep, voffB); PG8_STAGE(PG8_SA(0, 0), a2, voffA);
;             PG8_WAIT_V(8); PG8_WAIT_L(0); PG8_BAR; PG8_MMA(1, 0, At, B0); PG8_MMA(1, 1, At, B1); PG8_BAR; PG8_SCHED;
;     ...
; #pragma unroll
;         for (int a = 0; a < 2; ++a)
; #pragma unroll
;             for (int b = 0; b < 2; ++b)
; #pragma unroll
;                 for (int m = 0; m < 4; ++m)
; #pragma unroll
;                     for (int n = 0; n < 2; ++n) acc[a][b][m][n] = (f32x4){0.f, 0.f, 0.f, 0.f};
.Lz_enter_518:
	s_add_u32 s8, s52, 0x80
	s_addc_u32 s9, s53, 0
	s_add_u32 s52, s20, 0x100
	s_addc_u32 s53, s21, 0
	s_mov_b32 s20, 0
	s_add_i32 s69, s20, 2
	s_add_u32 s70, s8, 0x80
	s_addc_u32 s21, s9, 0
	s_cmp_eq_u32 s63, s20
	s_cselect_b32 s21, s49, s21
	s_cselect_b32 s20, s48, s70
	s_cselect_b32 s71, s51, s53
	s_cselect_b32 s70, s50, s52
	ds_read_b128 v[130:133], v185
	ds_read_b128 v[134:137], v185 offset:1024
	ds_read_b128 v[138:141], v185 offset:2048
	ds_read_b128 v[142:145], v185 offset:3072
	ds_read_b128 v[146:149], v185 offset:16384
	ds_read_b128 v[150:153], v185 offset:17408
	ds_read_b128 v[166:169], v185 offset:18432
	ds_read_b128 v[170:173], v185 offset:19456
	s_add_i32 m0, s56, 0xc000
	ds_read_b128 v[174:177], v189
	ds_read_b128 v[178:181], v189 offset:1024
	ds_read_b128 v[190:193], v189 offset:2048
	ds_read_b128 v[194:197], v189 offset:3072
	ds_read_b128 v[198:201], v189 offset:4096
	ds_read_b128 v[202:205], v189 offset:5120
	ds_read_b128 v[206:209], v189 offset:6144
	global_load_lds_dwordx4 v162, s[8:9]
	s_add_i32 m0, s56, 0xe000
	ds_read_b128 v[210:213], v189 offset:7168
	global_load_lds_dwordx4 v164, s[8:9]
	s_waitcnt vmcnt(8)
	s_waitcnt lgkmcnt(0)
	s_barrier
	s_setprio 1
	v_mfma_f32_16x16x32_bf16 v[126:129], v[130:133], v[174:177], 0
	v_mfma_f32_16x16x32_bf16 v[122:125], v[138:141], v[174:177], 0
	v_mfma_f32_16x16x32_bf16 v[110:113], v[130:133], v[190:193], 0
	v_mfma_f32_16x16x32_bf16 v[106:109], v[138:141], v[190:193], 0
	v_mfma_f32_16x16x32_bf16 v[94:97], v[130:133], v[198:201], 0
	v_mfma_f32_16x16x32_bf16 v[90:93], v[138:141], v[198:201], 0
	v_mfma_f32_16x16x32_bf16 v[78:81], v[130:133], v[206:209], 0
	v_mfma_f32_16x16x32_bf16 v[74:77], v[138:141], v[206:209], 0
	v_mfma_f32_16x16x32_bf16 v[126:129], v[134:137], v[178:181], v[126:129]
	v_mfma_f32_16x16x32_bf16 v[122:125], v[142:145], v[178:181], v[122:125]
	v_mfma_f32_16x16x32_bf16 v[110:113], v[134:137], v[194:197], v[110:113]
	v_mfma_f32_16x16x32_bf16 v[106:109], v[142:145], v[194:197], v[106:109]
	v_mfma_f32_16x16x32_bf16 v[94:97], v[134:137], v[202:205], v[94:97]
	v_mfma_f32_16x16x32_bf16 v[90:93], v[142:145], v[202:205], v[90:93]
	v_mfma_f32_16x16x32_bf16 v[78:81], v[134:137], v[210:213], v[78:81]
	v_mfma_f32_16x16x32_bf16 v[74:77], v[142:145], v[210:213], v[74:77]
	v_mfma_f32_16x16x32_bf16 v[118:121], v[146:149], v[174:177], 0
	v_mfma_f32_16x16x32_bf16 v[114:117], v[166:169], v[174:177], 0
	v_mfma_f32_16x16x32_bf16 v[102:105], v[146:149], v[190:193], 0
	v_mfma_f32_16x16x32_bf16 v[98:101], v[166:169], v[190:193], 0
	v_mfma_f32_16x16x32_bf16 v[86:89], v[146:149], v[198:201], 0
	v_mfma_f32_16x16x32_bf16 v[82:85], v[166:169], v[198:201], 0
	v_mfma_f32_16x16x32_bf16 v[70:73], v[146:149], v[206:209], 0
	v_mfma_f32_16x16x32_bf16 v[66:69], v[166:169], v[206:209], 0
	v_mfma_f32_16x16x32_bf16 v[118:121], v[150:153], v[178:181], v[118:121]
	v_mfma_f32_16x16x32_bf16 v[114:117], v[170:173], v[178:181], v[114:117]
	v_mfma_f32_16x16x32_bf16 v[102:105], v[150:153], v[194:197], v[102:105]
	v_mfma_f32_16x16x32_bf16 v[98:101], v[170:173], v[194:197], v[98:101]
	v_mfma_f32_16x16x32_bf16 v[86:89], v[150:153], v[202:205], v[86:89]
	v_mfma_f32_16x16x32_bf16 v[82:85], v[170:173], v[202:205], v[82:85]
	v_mfma_f32_16x16x32_bf16 v[70:73], v[150:153], v[210:213], v[70:73]
	v_mfma_f32_16x16x32_bf16 v[66:69], v[170:173], v[210:213], v[66:69]
	s_setprio 0
	s_barrier
	v_lshl_add_u64 v[186:187], s[70:71], 0, v[0:1]
	s_add_i32 m0, s30, 0x10000
	ds_read_b128 v[174:177], v189 offset:16384
	ds_read_b128 v[178:181], v189 offset:17408
	ds_read_b128 v[190:193], v189 offset:18432
	ds_read_b128 v[194:197], v189 offset:19456
	ds_read_b128 v[198:201], v189 offset:20480
	ds_read_b128 v[202:205], v189 offset:21504
	ds_read_b128 v[206:209], v189 offset:22528
	ds_read_b128 v[210:213], v189 offset:23552
	global_load_lds_dwordx4 v[186:187], off
	s_add_i32 m0, s30, 0x12000
	v_lshl_add_u64 v[214:215], s[70:71], 0, v[154:155]
	s_add_u32 s70, s70, s12
	s_addc_u32 s71, s71, s13
	global_load_lds_dwordx4 v[214:215], off
	v_lshl_add_u64 v[218:219], s[70:71], 0, v[0:1]
	s_add_i32 m0, s30, 0x14000
	v_lshl_add_u64 v[220:221], s[70:71], 0, v[154:155]
	global_load_lds_dwordx4 v[218:219], off
	s_add_i32 m0, s30, 0x16000
	v_lshl_add_u64 v[222:223], s[20:21], 0, v[158:159]
	global_load_lds_dwordx4 v[220:221], off
	s_mov_b32 m0, s56
	v_lshl_add_u64 v[224:225], s[20:21], 0, v[156:157]
	global_load_lds_dwordx4 v[222:223], off
	s_mov_b32 m0, s57
	s_nop 0
	global_load_lds_dwordx4 v[224:225], off
	s_waitcnt vmcnt(8)
	s_waitcnt lgkmcnt(0)
	s_barrier
	s_setprio 1
	v_mfma_f32_16x16x32_bf16 v[62:65], v[130:133], v[174:177], 0
	v_mfma_f32_16x16x32_bf16 v[58:61], v[138:141], v[174:177], 0
	v_mfma_f32_16x16x32_bf16 v[46:49], v[130:133], v[190:193], 0
	v_mfma_f32_16x16x32_bf16 v[42:45], v[138:141], v[190:193], 0
	v_mfma_f32_16x16x32_bf16 v[30:33], v[130:133], v[198:201], 0
	v_mfma_f32_16x16x32_bf16 v[26:29], v[138:141], v[198:201], 0
	v_mfma_f32_16x16x32_bf16 v[14:17], v[130:133], v[206:209], 0
	v_mfma_f32_16x16x32_bf16 v[10:13], v[138:141], v[206:209], 0
	v_mfma_f32_16x16x32_bf16 v[62:65], v[134:137], v[178:181], v[62:65]
	v_mfma_f32_16x16x32_bf16 v[58:61], v[142:145], v[178:181], v[58:61]
	v_mfma_f32_16x16x32_bf16 v[46:49], v[134:137], v[194:197], v[46:49]
	v_mfma_f32_16x16x32_bf16 v[42:45], v[142:145], v[194:197], v[42:45]
	v_mfma_f32_16x16x32_bf16 v[30:33], v[134:137], v[202:205], v[30:33]
	v_mfma_f32_16x16x32_bf16 v[26:29], v[142:145], v[202:205], v[26:29]
	v_mfma_f32_16x16x32_bf16 v[14:17], v[134:137], v[210:213], v[14:17]
	v_mfma_f32_16x16x32_bf16 v[10:13], v[142:145], v[210:213], v[10:13]
	v_mfma_f32_16x16x32_bf16 v[54:57], v[146:149], v[174:177], 0
	v_mfma_f32_16x16x32_bf16 v[50:53], v[166:169], v[174:177], 0
	v_mfma_f32_16x16x32_bf16 v[38:41], v[146:149], v[190:193], 0
	v_mfma_f32_16x16x32_bf16 v[34:37], v[166:169], v[190:193], 0
	v_mfma_f32_16x16x32_bf16 v[22:25], v[146:149], v[198:201], 0
	v_mfma_f32_16x16x32_bf16 v[18:21], v[166:169], v[198:201], 0
	v_mfma_f32_16x16x32_bf16 v[6:9], v[146:149], v[206:209], 0
	v_mfma_f32_16x16x32_bf16 v[2:5], v[166:169], v[206:209], 0
	v_mfma_f32_16x16x32_bf16 v[54:57], v[150:153], v[178:181], v[54:57]
	v_mfma_f32_16x16x32_bf16 v[50:53], v[170:173], v[178:181], v[50:53]
	v_mfma_f32_16x16x32_bf16 v[38:41], v[150:153], v[194:197], v[38:41]
	v_mfma_f32_16x16x32_bf16 v[34:37], v[170:173], v[194:197], v[34:37]
	v_mfma_f32_16x16x32_bf16 v[22:25], v[150:153], v[202:205], v[22:25]
	v_mfma_f32_16x16x32_bf16 v[18:21], v[170:173], v[202:205], v[18:21]
	v_mfma_f32_16x16x32_bf16 v[6:9], v[150:153], v[210:213], v[6:9]
	v_mfma_f32_16x16x32_bf16 v[2:5], v[170:173], v[210:213], v[2:5]
	s_setprio 0
	s_barrier
; #define PG8_STAGE(bufoff, gbase, voff) do { _Pragma("unroll") for (int _i = 0; _i < 2; ++_i) \
;         __builtin_amdgcn_global_load_lds((const unsigned*)((const char*)(gbase) + (voff)[_i]), (PG8_LAS unsigned*)(lds + (bufoff) + ldsw + _i * 8192), 16, 0, 0); } while (0)
; #define PG8_LDA(dst, b, h) do { _Pragma("unroll") for (int m = 0; m < 4; ++m) _Pragma("unroll") for (int k = 0; k < 2; ++k) dst[m][k] = *(const PG8_LAS bf16x8*)(lds + PG8_SA(b, h) + aoff + m * 2048 + k * 1024); } while (0)
; #define PG8_LDB(dst, b, h) do { _Pragma("unroll") for (int n = 0; n < 2; ++n) _Pragma("unroll") for (int k = 0; k < 2; ++k) dst[n][k] = *(const PG8_LAS bf16x8*)(lds + PG8_SB(b, h) + boff + n * 2048 + k * 1024); } while (0)
; #define PG8_MMA(ai, bj, At, Bt) do { __builtin_amdgcn_s_setprio(1); _Pragma("unroll") for (int m = 0; m < 4; ++m) _Pragma("unroll") for (int n = 0; n < 2; ++n) _Pragma("unroll") for (int k = 0; k < 2; ++k) \
;         acc[ai][bj][m][n] = __builtin_amdgcn_mfma_f32_16x16x32_bf16(Bt[n][k], At[m][k], acc[ai][bj][m][n], 0, 0, 0); __builtin_amdgcn_s_setprio(0); } while (0)
; #define PG8_WAIT_V(n) asm volatile("s_waitcnt vmcnt(" #n ")" ::: "memory")
; #define PG8_WAIT_L(n) asm volatile("s_waitcnt lgkmcnt(" #n ")" ::: "memory")
; #define PG8_BAR __builtin_amdgcn_s_barrier()
; #define PG8_SCHED __builtin_amdgcn_sched_barrier(0)
; template <class Epi, class Sched, bool ALIGN_EPI = false, bool SP2 = false>
; __device__ __forceinline__ void gemm_phase(PG8_LAS unsigned char* lds, const Gemm g, const Sched& S, const Epi& E) {
;     ...
;             PG8_LDB(B0, 1, 0); PG8_LDB(B1, 1, 1); PG8_SCHED; PG8_LDA(At, 1, 0); PG8_STAGE(PG8_SA(0, 1), a2 + hstep, voffA);
;             PG8_WAIT_V(8); PG8_WAIT_L(0); PG8_BAR; PG8_MMA(0, 0, At, B0); PG8_MMA(0, 1, At, B1); PG8_BAR; PG8_SCHED;
;             PG8_LDA(At, 1, 1); PG8_STAGE(PG8_SB(1, 0), b3, voffB); PG8_STAGE(PG8_SB(1, 1), b3 + hstep, voffB); PG8_STAGE(PG8_SA(1, 0), a3, voffA);
;             PG8_WAIT_V(8); PG8_WAIT_L(0); PG8_BAR; PG8_MMA(1, 0, At, B0); PG8_MMA(1, 1, At, B1); PG8_BAR; PG8_SCHED;
	ds_read_b128 v[130:133], v185 offset:32768
	ds_read_b128 v[134:137], v185 offset:33792
	ds_read_b128 v[138:141], v185 offset:34816
	ds_read_b128 v[142:145], v185 offset:35840
	ds_read_b128 v[146:149], v185 offset:49152
	ds_read_b128 v[150:153], v185 offset:50176
	ds_read_b128 v[166:169], v185 offset:51200
	ds_read_b128 v[170:173], v185 offset:52224
	s_mov_b32 m0, s58
	ds_read_b128 v[174:177], v189 offset:32768
	ds_read_b128 v[178:181], v189 offset:33792
	ds_read_b128 v[190:193], v189 offset:34816
	ds_read_b128 v[194:197], v189 offset:35840
	ds_read_b128 v[198:201], v189 offset:36864
	ds_read_b128 v[202:205], v189 offset:37888
	ds_read_b128 v[206:209], v189 offset:38912
	global_load_lds_dwordx4 v162, s[20:21]
	s_mov_b32 m0, s59
	ds_read_b128 v[210:213], v189 offset:39936
	global_load_lds_dwordx4 v164, s[20:21]
	s_waitcnt vmcnt(8)
	s_waitcnt lgkmcnt(0)
	s_barrier
	s_setprio 1
	v_mfma_f32_16x16x32_bf16 v[126:129], v[130:133], v[174:177], v[126:129]
	v_mfma_f32_16x16x32_bf16 v[122:125], v[138:141], v[174:177], v[122:125]
	v_mfma_f32_16x16x32_bf16 v[110:113], v[130:133], v[190:193], v[110:113]
	v_mfma_f32_16x16x32_bf16 v[106:109], v[138:141], v[190:193], v[106:109]
	v_mfma_f32_16x16x32_bf16 v[94:97], v[130:133], v[198:201], v[94:97]
	v_mfma_f32_16x16x32_bf16 v[90:93], v[138:141], v[198:201], v[90:93]
	v_mfma_f32_16x16x32_bf16 v[78:81], v[130:133], v[206:209], v[78:81]
	v_mfma_f32_16x16x32_bf16 v[74:77], v[138:141], v[206:209], v[74:77]
	v_mfma_f32_16x16x32_bf16 v[126:129], v[134:137], v[178:181], v[126:129]
	v_mfma_f32_16x16x32_bf16 v[122:125], v[142:145], v[178:181], v[122:125]
	v_mfma_f32_16x16x32_bf16 v[110:113], v[134:137], v[194:197], v[110:113]
	v_mfma_f32_16x16x32_bf16 v[106:109], v[142:145], v[194:197], v[106:109]
	v_mfma_f32_16x16x32_bf16 v[94:97], v[134:137], v[202:205], v[94:97]
	v_mfma_f32_16x16x32_bf16 v[90:93], v[142:145], v[202:205], v[90:93]
	v_mfma_f32_16x16x32_bf16 v[78:81], v[134:137], v[210:213], v[78:81]
	v_mfma_f32_16x16x32_bf16 v[74:77], v[142:145], v[210:213], v[74:77]
	v_mfma_f32_16x16x32_bf16 v[118:121], v[146:149], v[174:177], v[118:121]
	v_mfma_f32_16x16x32_bf16 v[114:117], v[166:169], v[174:177], v[114:117]
	v_mfma_f32_16x16x32_bf16 v[102:105], v[146:149], v[190:193], v[102:105]
	v_mfma_f32_16x16x32_bf16 v[98:101], v[166:169], v[190:193], v[98:101]
	v_mfma_f32_16x16x32_bf16 v[86:89], v[146:149], v[198:201], v[86:89]
	v_mfma_f32_16x16x32_bf16 v[82:85], v[166:169], v[198:201], v[82:85]
	v_mfma_f32_16x16x32_bf16 v[70:73], v[146:149], v[206:209], v[70:73]
	v_mfma_f32_16x16x32_bf16 v[66:69], v[166:169], v[206:209], v[66:69]
	v_mfma_f32_16x16x32_bf16 v[118:121], v[150:153], v[178:181], v[118:121]
	v_mfma_f32_16x16x32_bf16 v[114:117], v[170:173], v[178:181], v[114:117]
	v_mfma_f32_16x16x32_bf16 v[102:105], v[150:153], v[194:197], v[102:105]
	v_mfma_f32_16x16x32_bf16 v[98:101], v[170:173], v[194:197], v[98:101]
	v_mfma_f32_16x16x32_bf16 v[86:89], v[150:153], v[202:205], v[86:89]
	v_mfma_f32_16x16x32_bf16 v[82:85], v[170:173], v[202:205], v[82:85]
	v_mfma_f32_16x16x32_bf16 v[70:73], v[150:153], v[210:213], v[70:73]
	v_mfma_f32_16x16x32_bf16 v[66:69], v[170:173], v[210:213], v[66:69]
	s_setprio 0
	s_barrier
	s_add_i32 m0, s30, 0x17f80
	ds_read_b128 v[174:177], v189 offset:49152
	ds_read_b128 v[178:181], v189 offset:50176
	ds_read_b128 v[190:193], v189 offset:51200
	global_load_lds_dwordx4 v[186:187], off offset:128
	s_add_i32 m0, s30, 0x19f80
	ds_read_b128 v[194:197], v189 offset:52224
	global_load_lds_dwordx4 v[214:215], off offset:128
	s_add_i32 m0, s30, 0x1bf80
	ds_read_b128 v[198:201], v189 offset:53248
	global_load_lds_dwordx4 v[218:219], off offset:128
	s_add_i32 m0, s30, 0x1df80
	ds_read_b128 v[202:205], v189 offset:54272
	global_load_lds_dwordx4 v[220:221], off offset:128
	s_sub_i32 m0, s60, 0x80
	ds_read_b128 v[206:209], v189 offset:55296
	global_load_lds_dwordx4 v[222:223], off offset:128
	s_sub_i32 m0, s61, 0x80
	ds_read_b128 v[210:213], v189 offset:56320
	global_load_lds_dwordx4 v[224:225], off offset:128
	s_waitcnt vmcnt(8)
	s_waitcnt lgkmcnt(0)
	s_barrier
	s_setprio 1
	v_mfma_f32_16x16x32_bf16 v[62:65], v[130:133], v[174:177], v[62:65]
	v_mfma_f32_16x16x32_bf16 v[58:61], v[138:141], v[174:177], v[58:61]
	v_mfma_f32_16x16x32_bf16 v[46:49], v[130:133], v[190:193], v[46:49]
	v_mfma_f32_16x16x32_bf16 v[42:45], v[138:141], v[190:193], v[42:45]
	v_mfma_f32_16x16x32_bf16 v[30:33], v[130:133], v[198:201], v[30:33]
	v_mfma_f32_16x16x32_bf16 v[26:29], v[138:141], v[198:201], v[26:29]
	v_mfma_f32_16x16x32_bf16 v[14:17], v[130:133], v[206:209], v[14:17]
	v_mfma_f32_16x16x32_bf16 v[10:13], v[138:141], v[206:209], v[10:13]
	v_mfma_f32_16x16x32_bf16 v[62:65], v[134:137], v[178:181], v[62:65]
	v_mfma_f32_16x16x32_bf16 v[58:61], v[142:145], v[178:181], v[58:61]
	v_mfma_f32_16x16x32_bf16 v[46:49], v[134:137], v[194:197], v[46:49]
	v_mfma_f32_16x16x32_bf16 v[42:45], v[142:145], v[194:197], v[42:45]
	v_mfma_f32_16x16x32_bf16 v[30:33], v[134:137], v[202:205], v[30:33]
	v_mfma_f32_16x16x32_bf16 v[26:29], v[142:145], v[202:205], v[26:29]
	v_mfma_f32_16x16x32_bf16 v[14:17], v[134:137], v[210:213], v[14:17]
	v_mfma_f32_16x16x32_bf16 v[10:13], v[142:145], v[210:213], v[10:13]
	v_mfma_f32_16x16x32_bf16 v[54:57], v[146:149], v[174:177], v[54:57]
	v_mfma_f32_16x16x32_bf16 v[50:53], v[166:169], v[174:177], v[50:53]
	v_mfma_f32_16x16x32_bf16 v[38:41], v[146:149], v[190:193], v[38:41]
	v_mfma_f32_16x16x32_bf16 v[34:37], v[166:169], v[190:193], v[34:37]
	v_mfma_f32_16x16x32_bf16 v[22:25], v[146:149], v[198:201], v[22:25]
	v_mfma_f32_16x16x32_bf16 v[18:21], v[166:169], v[198:201], v[18:21]
	v_mfma_f32_16x16x32_bf16 v[6:9], v[146:149], v[206:209], v[6:9]
	v_mfma_f32_16x16x32_bf16 v[2:5], v[166:169], v[206:209], v[2:5]
	v_mfma_f32_16x16x32_bf16 v[54:57], v[150:153], v[178:181], v[54:57]
	v_mfma_f32_16x16x32_bf16 v[50:53], v[170:173], v[178:181], v[50:53]
	v_mfma_f32_16x16x32_bf16 v[38:41], v[150:153], v[194:197], v[38:41]
	v_mfma_f32_16x16x32_bf16 v[34:37], v[170:173], v[194:197], v[34:37]
	v_mfma_f32_16x16x32_bf16 v[22:25], v[150:153], v[202:205], v[22:25]
	v_mfma_f32_16x16x32_bf16 v[18:21], v[170:173], v[202:205], v[18:21]
	v_mfma_f32_16x16x32_bf16 v[6:9], v[150:153], v[210:213], v[6:9]
	v_mfma_f32_16x16x32_bf16 v[2:5], v[170:173], v[210:213], v[2:5]
	s_setprio 0
	s_barrier
	s_add_u32 s8, s8, 0x100
	s_addc_u32 s9, s9, 0
	s_add_u32 s52, s52, 0x100
	s_addc_u32 s53, s53, 0
	s_cmp_ge_i32 s69, s62
	s_mov_b32 s20, s69
	s_cbranch_scc1 .Lpz_exit_520

; #define PG8_BAR __builtin_amdgcn_s_barrier()
; template <class Epi, class Sched, bool ALIGN_EPI = false, bool SP2 = false>
; __device__ __forceinline__ void gemm_phase(PG8_LAS unsigned char* lds, const Gemm g, const Sched& S, const Epi& E) {
;     ...
;         if constexpr (ALIGN_EPI) { if (wr == 0) PG8_BAR; }
.Lpz_exit_520:
.LBB0_521:
	s_and_b64 vcc, exec, s[46:47]
	s_cbranch_vccz .LBB0_523
	s_barrier

; #define PG8_STAGE(bufoff, gbase, voff) do { _Pragma("unroll") for (int _i = 0; _i < 2; ++_i) \
;         __builtin_amdgcn_global_load_lds((const unsigned*)((const char*)(gbase) + (voff)[_i]), (PG8_LAS unsigned*)(lds + (bufoff) + ldsw + _i * 8192), 16, 0, 0); } while (0)
; #define PG8_LDA(dst, b, h) do { _Pragma("unroll") for (int m = 0; m < 4; ++m) _Pragma("unroll") for (int k = 0; k < 2; ++k) dst[m][k] = *(const PG8_LAS bf16x8*)(lds + PG8_SA(b, h) + aoff + m * 2048 + k * 1024); } while (0)
; #define PG8_LDB(dst, b, h) do { _Pragma("unroll") for (int n = 0; n < 2; ++n) _Pragma("unroll") for (int k = 0; k < 2; ++k) dst[n][k] = *(const PG8_LAS bf16x8*)(lds + PG8_SB(b, h) + boff + n * 2048 + k * 1024); } while (0)
; #define PG8_WAIT_V(n) asm volatile("s_waitcnt vmcnt(" #n ")" ::: "memory")
; #define PG8_WAIT_L(n) asm volatile("s_waitcnt lgkmcnt(" #n ")" ::: "memory")
; #define PG8_BAR __builtin_amdgcn_s_barrier()
; template <class Epi, class Sched, bool ALIGN_EPI = false, bool SP2 = false>
; __device__ __forceinline__ void gemm_phase(PG8_LAS unsigned char* lds, const Gemm g, const Sched& S, const Epi& E) {
;     ...
;         for (int t = 0; t < nt; t += 2) {
;             const bool last = (t == nt - 2);
;             const char* a1 = cA + (size_t)(t + 1) * kstep;
;             const char* a2 = last ? nA : cA + (size_t)(t + 2) * kstep; const char* b2 = last ? nB : cB + (size_t)(t + 2) * kstep;
;             const char* a3 = a2 + kstep; const char* b3 = b2 + kstep;
;             if (last && has_next) S.a_ready(nxt);
;             if constexpr (SP2) {
;             PG8_LDB(B0, 0, 0); PG8_LDB(B1, 0, 1); PG8_SCHED; PG8_LDA(At, 0, 0); PG8_STAGE(PG8_SA(1, 1), a1 + hstep, voffA);
;             PG8_WAIT_V(8); PG8_WAIT_L(0); PG8_BAR; PG8_MMA(0, 0, At, B0); PG8_MMA(0, 1, At, B1); PG8_BAR; PG8_SCHED;
;             PG8_LDA(At, 0, 1); PG8_STAGE(PG8_SB(0, 0), b2, voffB); PG8_STAGE(PG8_SB(0, 1), b2 + hstep, voffB); PG8_STAGE(PG8_SA(0, 0), a2, voffA);
;             PG8_WAIT_V(8); PG8_WAIT_L(0); PG8_BAR; PG8_MMA(1, 0, At, B0); PG8_MMA(1, 1, At, B1); PG8_BAR; PG8_SCHED;
;     ...
; #pragma unroll
;         for (int a = 0; a < 2; ++a)
; #pragma unroll
;             for (int b = 0; b < 2; ++b)
; #pragma unroll
;                 for (int m = 0; m < 4; ++m)
; #pragma unroll
;                     for (int n = 0; n < 2; ++n) acc[a][b][m][n] = (f32x4){0.f, 0.f, 0.f, 0.f};
.Lz_enter_568:
	s_add_u32 s10, s62, 0x80
	s_addc_u32 s11, s63, 0
	s_add_u32 s62, s20, 0x100
	s_addc_u32 s63, s21, 0
	s_mov_b32 s20, 0
	s_add_i32 s78, s20, 2
	s_add_u32 s79, s10, 0x80
	s_addc_u32 s21, s11, 0
	s_cmp_eq_u32 s68, s20
	s_cselect_b32 s21, s59, s21
	s_cselect_b32 s20, s58, s79
	s_cselect_b32 s81, s61, s63
	s_cselect_b32 s80, s60, s62
	ds_read_b128 v[82:85], v246
	ds_read_b128 v[98:101], v246 offset:1024
	ds_read_b128 v[102:105], v246 offset:2048
	ds_read_b128 v[106:109], v246 offset:3072
	ds_read_b128 v[146:149], v246 offset:16384
	ds_read_b128 v[150:153], v246 offset:17408
	ds_read_b128 v[154:157], v246 offset:18432
	ds_read_b128 v[158:161], v246 offset:19456
	s_add_i32 m0, s64, 0xc000
	ds_read_b128 v[162:165], v249
	ds_read_b128 v[166:169], v249 offset:1024
	ds_read_b128 v[170:173], v249 offset:2048
	ds_read_b128 v[174:177], v249 offset:3072
	ds_read_b128 v[178:181], v249 offset:4096
	ds_read_b128 v[182:185], v249 offset:5120
	ds_read_b128 v[186:189], v249 offset:6144
	global_load_lds_dwordx4 v224, s[10:11]
	s_add_i32 m0, s64, 0xe000
	ds_read_b128 v[190:193], v249 offset:7168
	global_load_lds_dwordx4 v226, s[10:11]
	s_waitcnt vmcnt(8)
	s_waitcnt lgkmcnt(0)
	s_barrier
	s_setprio 1
	v_mfma_f32_16x16x32_bf16 v[142:145], v[82:85], v[162:165], 0
	v_mfma_f32_16x16x32_bf16 v[138:141], v[102:105], v[162:165], 0
	v_mfma_f32_16x16x32_bf16 v[126:129], v[82:85], v[170:173], 0
	v_mfma_f32_16x16x32_bf16 v[122:125], v[102:105], v[170:173], 0
	v_mfma_f32_16x16x32_bf16 v[110:113], v[82:85], v[178:181], 0
	v_mfma_f32_16x16x32_bf16 v[94:97], v[102:105], v[178:181], 0
	v_mfma_f32_16x16x32_bf16 v[78:81], v[82:85], v[186:189], 0
	v_mfma_f32_16x16x32_bf16 v[74:77], v[102:105], v[186:189], 0
	v_mfma_f32_16x16x32_bf16 v[142:145], v[98:101], v[166:169], v[142:145]
	v_mfma_f32_16x16x32_bf16 v[138:141], v[106:109], v[166:169], v[138:141]
	v_mfma_f32_16x16x32_bf16 v[126:129], v[98:101], v[174:177], v[126:129]
	v_mfma_f32_16x16x32_bf16 v[122:125], v[106:109], v[174:177], v[122:125]
	v_mfma_f32_16x16x32_bf16 v[110:113], v[98:101], v[182:185], v[110:113]
	v_mfma_f32_16x16x32_bf16 v[94:97], v[106:109], v[182:185], v[94:97]
	v_mfma_f32_16x16x32_bf16 v[78:81], v[98:101], v[190:193], v[78:81]
	v_mfma_f32_16x16x32_bf16 v[74:77], v[106:109], v[190:193], v[74:77]
	v_mfma_f32_16x16x32_bf16 v[134:137], v[146:149], v[162:165], 0
	v_mfma_f32_16x16x32_bf16 v[130:133], v[154:157], v[162:165], 0
	v_mfma_f32_16x16x32_bf16 v[118:121], v[146:149], v[170:173], 0
	v_mfma_f32_16x16x32_bf16 v[114:117], v[154:157], v[170:173], 0
	v_mfma_f32_16x16x32_bf16 v[90:93], v[146:149], v[178:181], 0
	v_mfma_f32_16x16x32_bf16 v[86:89], v[154:157], v[178:181], 0
	v_mfma_f32_16x16x32_bf16 v[70:73], v[146:149], v[186:189], 0
	v_mfma_f32_16x16x32_bf16 v[66:69], v[154:157], v[186:189], 0
	v_mfma_f32_16x16x32_bf16 v[134:137], v[150:153], v[166:169], v[134:137]
	v_mfma_f32_16x16x32_bf16 v[130:133], v[158:161], v[166:169], v[130:133]
	v_mfma_f32_16x16x32_bf16 v[118:121], v[150:153], v[174:177], v[118:121]
	v_mfma_f32_16x16x32_bf16 v[114:117], v[158:161], v[174:177], v[114:117]
	v_mfma_f32_16x16x32_bf16 v[90:93], v[150:153], v[182:185], v[90:93]
	v_mfma_f32_16x16x32_bf16 v[86:89], v[158:161], v[182:185], v[86:89]
	v_mfma_f32_16x16x32_bf16 v[70:73], v[150:153], v[190:193], v[70:73]
	v_mfma_f32_16x16x32_bf16 v[66:69], v[158:161], v[190:193], v[66:69]
	s_setprio 0
	s_barrier
	v_lshl_add_u64 v[194:195], s[80:81], 0, v[0:1]
	s_add_i32 m0, s22, 0x10000
	ds_read_b128 v[162:165], v249 offset:16384
	ds_read_b128 v[166:169], v249 offset:17408
	ds_read_b128 v[170:173], v249 offset:18432
	ds_read_b128 v[174:177], v249 offset:19456
	ds_read_b128 v[178:181], v249 offset:20480
	ds_read_b128 v[182:185], v249 offset:21504
	ds_read_b128 v[186:189], v249 offset:22528
	ds_read_b128 v[190:193], v249 offset:23552
	global_load_lds_dwordx4 v[194:195], off
	s_add_i32 m0, s22, 0x12000
	v_lshl_add_u64 v[196:197], s[80:81], 0, v[218:219]
	s_add_u32 s80, s80, s46
	s_addc_u32 s81, s81, s47
	global_load_lds_dwordx4 v[196:197], off
	v_lshl_add_u64 v[198:199], s[80:81], 0, v[0:1]
	s_add_i32 m0, s22, 0x14000
	v_lshl_add_u64 v[200:201], s[80:81], 0, v[218:219]
	global_load_lds_dwordx4 v[198:199], off
	s_add_i32 m0, s22, 0x16000
	v_lshl_add_u64 v[202:203], s[20:21], 0, v[0:1]
	global_load_lds_dwordx4 v[200:201], off
	s_mov_b32 m0, s64
	v_lshl_add_u64 v[204:205], s[20:21], 0, v[218:219]
	global_load_lds_dwordx4 v[202:203], off
	s_mov_b32 m0, s30
	s_nop 0
	global_load_lds_dwordx4 v[204:205], off
	s_waitcnt vmcnt(8)
	s_waitcnt lgkmcnt(0)
	s_barrier
	s_setprio 1
	v_mfma_f32_16x16x32_bf16 v[62:65], v[82:85], v[162:165], 0
	v_mfma_f32_16x16x32_bf16 v[58:61], v[102:105], v[162:165], 0
	v_mfma_f32_16x16x32_bf16 v[46:49], v[82:85], v[170:173], 0
	v_mfma_f32_16x16x32_bf16 v[42:45], v[102:105], v[170:173], 0
	v_mfma_f32_16x16x32_bf16 v[30:33], v[82:85], v[178:181], 0
	v_mfma_f32_16x16x32_bf16 v[26:29], v[102:105], v[178:181], 0
	v_mfma_f32_16x16x32_bf16 v[14:17], v[82:85], v[186:189], 0
	v_mfma_f32_16x16x32_bf16 v[10:13], v[102:105], v[186:189], 0
	v_mfma_f32_16x16x32_bf16 v[62:65], v[98:101], v[166:169], v[62:65]
	v_mfma_f32_16x16x32_bf16 v[58:61], v[106:109], v[166:169], v[58:61]
	v_mfma_f32_16x16x32_bf16 v[46:49], v[98:101], v[174:177], v[46:49]
	v_mfma_f32_16x16x32_bf16 v[42:45], v[106:109], v[174:177], v[42:45]
	v_mfma_f32_16x16x32_bf16 v[30:33], v[98:101], v[182:185], v[30:33]
	v_mfma_f32_16x16x32_bf16 v[26:29], v[106:109], v[182:185], v[26:29]
	v_mfma_f32_16x16x32_bf16 v[14:17], v[98:101], v[190:193], v[14:17]
	v_mfma_f32_16x16x32_bf16 v[10:13], v[106:109], v[190:193], v[10:13]
	v_mfma_f32_16x16x32_bf16 v[54:57], v[146:149], v[162:165], 0
	v_mfma_f32_16x16x32_bf16 v[50:53], v[154:157], v[162:165], 0
	v_mfma_f32_16x16x32_bf16 v[38:41], v[146:149], v[170:173], 0
	v_mfma_f32_16x16x32_bf16 v[34:37], v[154:157], v[170:173], 0
	v_mfma_f32_16x16x32_bf16 v[22:25], v[146:149], v[178:181], 0
	v_mfma_f32_16x16x32_bf16 v[18:21], v[154:157], v[178:181], 0
	v_mfma_f32_16x16x32_bf16 v[6:9], v[146:149], v[186:189], 0
	v_mfma_f32_16x16x32_bf16 v[2:5], v[154:157], v[186:189], 0
	v_mfma_f32_16x16x32_bf16 v[54:57], v[150:153], v[166:169], v[54:57]
	v_mfma_f32_16x16x32_bf16 v[50:53], v[158:161], v[166:169], v[50:53]
	v_mfma_f32_16x16x32_bf16 v[38:41], v[150:153], v[174:177], v[38:41]
	v_mfma_f32_16x16x32_bf16 v[34:37], v[158:161], v[174:177], v[34:37]
	v_mfma_f32_16x16x32_bf16 v[22:25], v[150:153], v[182:185], v[22:25]
	v_mfma_f32_16x16x32_bf16 v[18:21], v[158:161], v[182:185], v[18:21]
	v_mfma_f32_16x16x32_bf16 v[6:9], v[150:153], v[190:193], v[6:9]
	v_mfma_f32_16x16x32_bf16 v[2:5], v[158:161], v[190:193], v[2:5]
	s_setprio 0
	s_barrier
; #define PG8_STAGE(bufoff, gbase, voff) do { _Pragma("unroll") for (int _i = 0; _i < 2; ++_i) \
;         __builtin_amdgcn_global_load_lds((const unsigned*)((const char*)(gbase) + (voff)[_i]), (PG8_LAS unsigned*)(lds + (bufoff) + ldsw + _i * 8192), 16, 0, 0); } while (0)
; #define PG8_LDA(dst, b, h) do { _Pragma("unroll") for (int m = 0; m < 4; ++m) _Pragma("unroll") for (int k = 0; k < 2; ++k) dst[m][k] = *(const PG8_LAS bf16x8*)(lds + PG8_SA(b, h) + aoff + m * 2048 + k * 1024); } while (0)
; #define PG8_LDB(dst, b, h) do { _Pragma("unroll") for (int n = 0; n < 2; ++n) _Pragma("unroll") for (int k = 0; k < 2; ++k) dst[n][k] = *(const PG8_LAS bf16x8*)(lds + PG8_SB(b, h) + boff + n * 2048 + k * 1024); } while (0)
; #define PG8_MMA(ai, bj, At, Bt) do { __builtin_amdgcn_s_setprio(1); _Pragma("unroll") for (int m = 0; m < 4; ++m) _Pragma("unroll") for (int n = 0; n < 2; ++n) _Pragma("unroll") for (int k = 0; k < 2; ++k) \
;         acc[ai][bj][m][n] = __builtin_amdgcn_mfma_f32_16x16x32_bf16(Bt[n][k], At[m][k], acc[ai][bj][m][n], 0, 0, 0); __builtin_amdgcn_s_setprio(0); } while (0)
; #define PG8_WAIT_V(n) asm volatile("s_waitcnt vmcnt(" #n ")" ::: "memory")
; #define PG8_WAIT_L(n) asm volatile("s_waitcnt lgkmcnt(" #n ")" ::: "memory")
; #define PG8_BAR __builtin_amdgcn_s_barrier()
; #define PG8_SCHED __builtin_amdgcn_sched_barrier(0)
; template <class Epi, class Sched, bool ALIGN_EPI = false, bool SP2 = false>
; __device__ __forceinline__ void gemm_phase(PG8_LAS unsigned char* lds, const Gemm g, const Sched& S, const Epi& E) {
;     ...
;             PG8_LDB(B0, 1, 0); PG8_LDB(B1, 1, 1); PG8_SCHED; PG8_LDA(At, 1, 0); PG8_STAGE(PG8_SA(0, 1), a2 + hstep, voffA);
;             PG8_WAIT_V(8); PG8_WAIT_L(0); PG8_BAR; PG8_MMA(0, 0, At, B0); PG8_MMA(0, 1, At, B1); PG8_BAR; PG8_SCHED;
;             PG8_LDA(At, 1, 1); PG8_STAGE(PG8_SB(1, 0), b3, voffB); PG8_STAGE(PG8_SB(1, 1), b3 + hstep, voffB); PG8_STAGE(PG8_SA(1, 0), a3, voffA);
;             PG8_WAIT_V(8); PG8_WAIT_L(0); PG8_BAR; PG8_MMA(1, 0, At, B0); PG8_MMA(1, 1, At, B1); PG8_BAR; PG8_SCHED;
	ds_read_b128 v[82:85], v246 offset:32768
	ds_read_b128 v[98:101], v246 offset:33792
	ds_read_b128 v[102:105], v246 offset:34816
	ds_read_b128 v[106:109], v246 offset:35840
	ds_read_b128 v[146:149], v246 offset:49152
	ds_read_b128 v[150:153], v246 offset:50176
	ds_read_b128 v[154:157], v246 offset:51200
	ds_read_b128 v[158:161], v246 offset:52224
	s_mov_b32 m0, s31
	ds_read_b128 v[162:165], v249 offset:32768
	ds_read_b128 v[166:169], v249 offset:33792
	ds_read_b128 v[170:173], v249 offset:34816
	ds_read_b128 v[174:177], v249 offset:35840
	ds_read_b128 v[178:181], v249 offset:36864
	ds_read_b128 v[182:185], v249 offset:37888
	ds_read_b128 v[186:189], v249 offset:38912
	global_load_lds_dwordx4 v224, s[20:21]
	s_mov_b32 m0, s33
	ds_read_b128 v[190:193], v249 offset:39936
	global_load_lds_dwordx4 v226, s[20:21]
	s_waitcnt vmcnt(8)
	s_waitcnt lgkmcnt(0)
	s_barrier
	s_setprio 1
	v_mfma_f32_16x16x32_bf16 v[142:145], v[82:85], v[162:165], v[142:145]
	v_mfma_f32_16x16x32_bf16 v[138:141], v[102:105], v[162:165], v[138:141]
	v_mfma_f32_16x16x32_bf16 v[126:129], v[82:85], v[170:173], v[126:129]
	v_mfma_f32_16x16x32_bf16 v[122:125], v[102:105], v[170:173], v[122:125]
	v_mfma_f32_16x16x32_bf16 v[110:113], v[82:85], v[178:181], v[110:113]
	v_mfma_f32_16x16x32_bf16 v[94:97], v[102:105], v[178:181], v[94:97]
	v_mfma_f32_16x16x32_bf16 v[78:81], v[82:85], v[186:189], v[78:81]
	v_mfma_f32_16x16x32_bf16 v[74:77], v[102:105], v[186:189], v[74:77]
	v_mfma_f32_16x16x32_bf16 v[142:145], v[98:101], v[166:169], v[142:145]
	v_mfma_f32_16x16x32_bf16 v[138:141], v[106:109], v[166:169], v[138:141]
	v_mfma_f32_16x16x32_bf16 v[126:129], v[98:101], v[174:177], v[126:129]
	v_mfma_f32_16x16x32_bf16 v[122:125], v[106:109], v[174:177], v[122:125]
	v_mfma_f32_16x16x32_bf16 v[110:113], v[98:101], v[182:185], v[110:113]
	v_mfma_f32_16x16x32_bf16 v[94:97], v[106:109], v[182:185], v[94:97]
	v_mfma_f32_16x16x32_bf16 v[78:81], v[98:101], v[190:193], v[78:81]
	v_mfma_f32_16x16x32_bf16 v[74:77], v[106:109], v[190:193], v[74:77]
	v_mfma_f32_16x16x32_bf16 v[134:137], v[146:149], v[162:165], v[134:137]
	v_mfma_f32_16x16x32_bf16 v[130:133], v[154:157], v[162:165], v[130:133]
	v_mfma_f32_16x16x32_bf16 v[118:121], v[146:149], v[170:173], v[118:121]
	v_mfma_f32_16x16x32_bf16 v[114:117], v[154:157], v[170:173], v[114:117]
	v_mfma_f32_16x16x32_bf16 v[90:93], v[146:149], v[178:181], v[90:93]
	v_mfma_f32_16x16x32_bf16 v[86:89], v[154:157], v[178:181], v[86:89]
	v_mfma_f32_16x16x32_bf16 v[70:73], v[146:149], v[186:189], v[70:73]
	v_mfma_f32_16x16x32_bf16 v[66:69], v[154:157], v[186:189], v[66:69]
	v_mfma_f32_16x16x32_bf16 v[134:137], v[150:153], v[166:169], v[134:137]
	v_mfma_f32_16x16x32_bf16 v[130:133], v[158:161], v[166:169], v[130:133]
	v_mfma_f32_16x16x32_bf16 v[118:121], v[150:153], v[174:177], v[118:121]
	v_mfma_f32_16x16x32_bf16 v[114:117], v[158:161], v[174:177], v[114:117]
	v_mfma_f32_16x16x32_bf16 v[90:93], v[150:153], v[182:185], v[90:93]
	v_mfma_f32_16x16x32_bf16 v[86:89], v[158:161], v[182:185], v[86:89]
	v_mfma_f32_16x16x32_bf16 v[70:73], v[150:153], v[190:193], v[70:73]
	v_mfma_f32_16x16x32_bf16 v[66:69], v[158:161], v[190:193], v[66:69]
	s_setprio 0
	s_barrier
	s_add_i32 m0, s22, 0x17f80
	ds_read_b128 v[162:165], v249 offset:49152
	ds_read_b128 v[166:169], v249 offset:50176
	ds_read_b128 v[170:173], v249 offset:51200
	global_load_lds_dwordx4 v[194:195], off offset:128
	s_add_i32 m0, s22, 0x19f80
	ds_read_b128 v[174:177], v249 offset:52224
	global_load_lds_dwordx4 v[196:197], off offset:128
	s_add_i32 m0, s22, 0x1bf80
	ds_read_b128 v[178:181], v249 offset:53248
	global_load_lds_dwordx4 v[198:199], off offset:128
	s_add_i32 m0, s22, 0x1df80
	ds_read_b128 v[182:185], v249 offset:54272
	global_load_lds_dwordx4 v[200:201], off offset:128
	s_sub_i32 m0, s39, 0x80
	ds_read_b128 v[186:189], v249 offset:55296
	global_load_lds_dwordx4 v[202:203], off offset:128
	s_sub_i32 m0, s65, 0x80
	ds_read_b128 v[190:193], v249 offset:56320
	global_load_lds_dwordx4 v[204:205], off offset:128
	s_waitcnt vmcnt(8)
	s_waitcnt lgkmcnt(0)
	s_barrier
	s_setprio 1
	v_mfma_f32_16x16x32_bf16 v[62:65], v[82:85], v[162:165], v[62:65]
	v_mfma_f32_16x16x32_bf16 v[58:61], v[102:105], v[162:165], v[58:61]
	v_mfma_f32_16x16x32_bf16 v[46:49], v[82:85], v[170:173], v[46:49]
	v_mfma_f32_16x16x32_bf16 v[42:45], v[102:105], v[170:173], v[42:45]
	v_mfma_f32_16x16x32_bf16 v[30:33], v[82:85], v[178:181], v[30:33]
	v_mfma_f32_16x16x32_bf16 v[26:29], v[102:105], v[178:181], v[26:29]
	v_mfma_f32_16x16x32_bf16 v[14:17], v[82:85], v[186:189], v[14:17]
	v_mfma_f32_16x16x32_bf16 v[10:13], v[102:105], v[186:189], v[10:13]
	v_mfma_f32_16x16x32_bf16 v[62:65], v[98:101], v[166:169], v[62:65]
	v_mfma_f32_16x16x32_bf16 v[58:61], v[106:109], v[166:169], v[58:61]
	v_mfma_f32_16x16x32_bf16 v[46:49], v[98:101], v[174:177], v[46:49]
	v_mfma_f32_16x16x32_bf16 v[42:45], v[106:109], v[174:177], v[42:45]
	v_mfma_f32_16x16x32_bf16 v[30:33], v[98:101], v[182:185], v[30:33]
	v_mfma_f32_16x16x32_bf16 v[26:29], v[106:109], v[182:185], v[26:29]
	v_mfma_f32_16x16x32_bf16 v[14:17], v[98:101], v[190:193], v[14:17]
	v_mfma_f32_16x16x32_bf16 v[10:13], v[106:109], v[190:193], v[10:13]
	v_mfma_f32_16x16x32_bf16 v[54:57], v[146:149], v[162:165], v[54:57]
	v_mfma_f32_16x16x32_bf16 v[50:53], v[154:157], v[162:165], v[50:53]
	v_mfma_f32_16x16x32_bf16 v[38:41], v[146:149], v[170:173], v[38:41]
	v_mfma_f32_16x16x32_bf16 v[34:37], v[154:157], v[170:173], v[34:37]
	v_mfma_f32_16x16x32_bf16 v[22:25], v[146:149], v[178:181], v[22:25]
	v_mfma_f32_16x16x32_bf16 v[18:21], v[154:157], v[178:181], v[18:21]
	v_mfma_f32_16x16x32_bf16 v[6:9], v[146:149], v[186:189], v[6:9]
	v_mfma_f32_16x16x32_bf16 v[2:5], v[154:157], v[186:189], v[2:5]
	v_mfma_f32_16x16x32_bf16 v[54:57], v[150:153], v[166:169], v[54:57]
	v_mfma_f32_16x16x32_bf16 v[50:53], v[158:161], v[166:169], v[50:53]
	v_mfma_f32_16x16x32_bf16 v[38:41], v[150:153], v[174:177], v[38:41]
	v_mfma_f32_16x16x32_bf16 v[34:37], v[158:161], v[174:177], v[34:37]
	v_mfma_f32_16x16x32_bf16 v[22:25], v[150:153], v[182:185], v[22:25]
	v_mfma_f32_16x16x32_bf16 v[18:21], v[158:161], v[182:185], v[18:21]
	v_mfma_f32_16x16x32_bf16 v[6:9], v[150:153], v[190:193], v[6:9]
	v_mfma_f32_16x16x32_bf16 v[2:5], v[158:161], v[190:193], v[2:5]
	s_setprio 0
	s_barrier
	s_add_u32 s10, s10, 0x100
	s_addc_u32 s11, s11, 0
	s_add_u32 s62, s62, 0x100
	s_addc_u32 s63, s63, 0
	s_cmp_ge_i32 s78, s67
	s_mov_b32 s20, s78
	s_cbranch_scc1 .Lpz_exit_570

; #define PG8_BAR __builtin_amdgcn_s_barrier()
; template <class Epi, class Sched, bool ALIGN_EPI = false, bool SP2 = false>
; __device__ __forceinline__ void gemm_phase(PG8_LAS unsigned char* lds, const Gemm g, const Sched& S, const Epi& E) {
;     ...
;         if constexpr (ALIGN_EPI) { if (wr == 0) PG8_BAR; }
.Lpz_exit_570:
.LBB0_571:
	s_and_b64 vcc, exec, s[52:53]
	s_cbranch_vccz .LBB0_573
	s_barrier

; #define PG8_STAGE(bufoff, gbase, voff) do { _Pragma("unroll") for (int _i = 0; _i < 2; ++_i) \
;         __builtin_amdgcn_global_load_lds((const unsigned*)((const char*)(gbase) + (voff)[_i]), (PG8_LAS unsigned*)(lds + (bufoff) + ldsw + _i * 8192), 16, 0, 0); } while (0)
; #define PG8_LDA(dst, b, h) do { _Pragma("unroll") for (int m = 0; m < 4; ++m) _Pragma("unroll") for (int k = 0; k < 2; ++k) dst[m][k] = *(const PG8_LAS bf16x8*)(lds + PG8_SA(b, h) + aoff + m * 2048 + k * 1024); } while (0)
; #define PG8_LDB(dst, b, h) do { _Pragma("unroll") for (int n = 0; n < 2; ++n) _Pragma("unroll") for (int k = 0; k < 2; ++k) dst[n][k] = *(const PG8_LAS bf16x8*)(lds + PG8_SB(b, h) + boff + n * 2048 + k * 1024); } while (0)
; #define PG8_WAIT_V(n) asm volatile("s_waitcnt vmcnt(" #n ")" ::: "memory")
; #define PG8_WAIT_L(n) asm volatile("s_waitcnt lgkmcnt(" #n ")" ::: "memory")
; #define PG8_BAR __builtin_amdgcn_s_barrier()
; template <class Epi, class Sched, bool ALIGN_EPI = false, bool SP2 = false>
; __device__ __forceinline__ void gemm_phase(PG8_LAS unsigned char* lds, const Gemm g, const Sched& S, const Epi& E) {
;     ...
;         for (int t = 0; t < nt; t += 2) {
;             const bool last = (t == nt - 2);
;             const char* a1 = cA + (size_t)(t + 1) * kstep;
;             const char* a2 = last ? nA : cA + (size_t)(t + 2) * kstep; const char* b2 = last ? nB : cB + (size_t)(t + 2) * kstep;
;             const char* a3 = a2 + kstep; const char* b3 = b2 + kstep;
;             if (last && has_next) S.a_ready(nxt);
;             if constexpr (SP2) {
;             PG8_LDB(B0, 0, 0); PG8_LDB(B1, 0, 1); PG8_SCHED; PG8_LDA(At, 0, 0); PG8_STAGE(PG8_SA(1, 1), a1 + hstep, voffA);
;             PG8_WAIT_V(8); PG8_WAIT_L(0); PG8_BAR; PG8_MMA(0, 0, At, B0); PG8_MMA(0, 1, At, B1); PG8_BAR; PG8_SCHED;
;             PG8_LDA(At, 0, 1); PG8_STAGE(PG8_SB(0, 0), b2, voffB); PG8_STAGE(PG8_SB(0, 1), b2 + hstep, voffB); PG8_STAGE(PG8_SA(0, 0), a2, voffA);
;             PG8_WAIT_V(8); PG8_WAIT_L(0); PG8_BAR; PG8_MMA(1, 0, At, B0); PG8_MMA(1, 1, At, B1); PG8_BAR; PG8_SCHED;
;     ...
; #pragma unroll
;         for (int a = 0; a < 2; ++a)
; #pragma unroll
;             for (int b = 0; b < 2; ++b)
; #pragma unroll
;                 for (int m = 0; m < 4; ++m)
; #pragma unroll
;                     for (int n = 0; n < 2; ++n) acc[a][b][m][n] = (f32x4){0.f, 0.f, 0.f, 0.f};
.Lz_enter_639:
	s_add_u32 s8, s52, 0x80
	s_addc_u32 s9, s53, 0
	s_add_u32 s52, s20, 0x100
	s_addc_u32 s53, s21, 0
	s_mov_b32 s20, 0
	s_add_i32 s68, s20, 2
	s_add_u32 s69, s8, 0x80
	s_addc_u32 s21, s9, 0
	s_cmp_eq_u32 s63, s20
	s_cselect_b32 s21, s49, s21
	s_cselect_b32 s20, s48, s69
	s_cselect_b32 s71, s51, s53
	s_cselect_b32 s70, s50, s52
	ds_read_b128 v[130:133], v181
	ds_read_b128 v[134:137], v181 offset:1024
	ds_read_b128 v[138:141], v181 offset:2048
	ds_read_b128 v[142:145], v181 offset:3072
	ds_read_b128 v[146:149], v181 offset:16384
	ds_read_b128 v[150:153], v181 offset:17408
	ds_read_b128 v[166:169], v181 offset:18432
	ds_read_b128 v[170:173], v181 offset:19456
	s_add_i32 m0, s55, 0xc000
	ds_read_b128 v[174:177], v183
	ds_read_b128 v[184:187], v183 offset:1024
	ds_read_b128 v[188:191], v183 offset:2048
	ds_read_b128 v[192:195], v183 offset:3072
	ds_read_b128 v[196:199], v183 offset:4096
	ds_read_b128 v[200:203], v183 offset:5120
	ds_read_b128 v[204:207], v183 offset:6144
	global_load_lds_dwordx4 v162, s[8:9]
	s_add_i32 m0, s55, 0xe000
	ds_read_b128 v[208:211], v183 offset:7168
	global_load_lds_dwordx4 v164, s[8:9]
	s_waitcnt vmcnt(8)
	s_waitcnt lgkmcnt(0)
	s_barrier
	s_setprio 1
	v_mfma_f32_16x16x32_bf16 v[122:125], v[130:133], v[174:177], 0
	v_mfma_f32_16x16x32_bf16 v[118:121], v[138:141], v[174:177], 0
	v_mfma_f32_16x16x32_bf16 v[106:109], v[130:133], v[188:191], 0
	v_mfma_f32_16x16x32_bf16 v[102:105], v[138:141], v[188:191], 0
	v_mfma_f32_16x16x32_bf16 v[90:93], v[130:133], v[196:199], 0
	v_mfma_f32_16x16x32_bf16 v[86:89], v[138:141], v[196:199], 0
	v_mfma_f32_16x16x32_bf16 v[74:77], v[130:133], v[204:207], 0
	v_mfma_f32_16x16x32_bf16 v[70:73], v[138:141], v[204:207], 0
	v_mfma_f32_16x16x32_bf16 v[122:125], v[134:137], v[184:187], v[122:125]
	v_mfma_f32_16x16x32_bf16 v[118:121], v[142:145], v[184:187], v[118:121]
	v_mfma_f32_16x16x32_bf16 v[106:109], v[134:137], v[192:195], v[106:109]
	v_mfma_f32_16x16x32_bf16 v[102:105], v[142:145], v[192:195], v[102:105]
	v_mfma_f32_16x16x32_bf16 v[90:93], v[134:137], v[200:203], v[90:93]
	v_mfma_f32_16x16x32_bf16 v[86:89], v[142:145], v[200:203], v[86:89]
	v_mfma_f32_16x16x32_bf16 v[74:77], v[134:137], v[208:211], v[74:77]
	v_mfma_f32_16x16x32_bf16 v[70:73], v[142:145], v[208:211], v[70:73]
	v_mfma_f32_16x16x32_bf16 v[126:129], v[146:149], v[174:177], 0
	v_mfma_f32_16x16x32_bf16 v[114:117], v[166:169], v[174:177], 0
	v_mfma_f32_16x16x32_bf16 v[110:113], v[146:149], v[188:191], 0
	v_mfma_f32_16x16x32_bf16 v[98:101], v[166:169], v[188:191], 0
	v_mfma_f32_16x16x32_bf16 v[94:97], v[146:149], v[196:199], 0
	v_mfma_f32_16x16x32_bf16 v[82:85], v[166:169], v[196:199], 0
	v_mfma_f32_16x16x32_bf16 v[78:81], v[146:149], v[204:207], 0
	v_mfma_f32_16x16x32_bf16 v[66:69], v[166:169], v[204:207], 0
	v_mfma_f32_16x16x32_bf16 v[126:129], v[150:153], v[184:187], v[126:129]
	v_mfma_f32_16x16x32_bf16 v[114:117], v[170:173], v[184:187], v[114:117]
	v_mfma_f32_16x16x32_bf16 v[110:113], v[150:153], v[192:195], v[110:113]
	v_mfma_f32_16x16x32_bf16 v[98:101], v[170:173], v[192:195], v[98:101]
	v_mfma_f32_16x16x32_bf16 v[94:97], v[150:153], v[200:203], v[94:97]
	v_mfma_f32_16x16x32_bf16 v[82:85], v[170:173], v[200:203], v[82:85]
	v_mfma_f32_16x16x32_bf16 v[78:81], v[150:153], v[208:211], v[78:81]
	v_mfma_f32_16x16x32_bf16 v[66:69], v[170:173], v[208:211], v[66:69]
	s_setprio 0
	s_barrier
	v_lshl_add_u64 v[178:179], s[70:71], 0, v[0:1]
	s_add_i32 m0, s23, 0x10000
	ds_read_b128 v[174:177], v183 offset:16384
	ds_read_b128 v[184:187], v183 offset:17408
	ds_read_b128 v[188:191], v183 offset:18432
	ds_read_b128 v[192:195], v183 offset:19456
	ds_read_b128 v[196:199], v183 offset:20480
	ds_read_b128 v[200:203], v183 offset:21504
	ds_read_b128 v[204:207], v183 offset:22528
	ds_read_b128 v[208:211], v183 offset:23552
	global_load_lds_dwordx4 v[178:179], off
	s_add_i32 m0, s23, 0x12000
	v_lshl_add_u64 v[212:213], s[70:71], 0, v[154:155]
	s_add_u32 s70, s70, s10
	s_addc_u32 s71, s71, s11
	global_load_lds_dwordx4 v[212:213], off
	v_lshl_add_u64 v[214:215], s[70:71], 0, v[0:1]
	s_add_i32 m0, s23, 0x14000
	v_lshl_add_u64 v[218:219], s[70:71], 0, v[154:155]
	global_load_lds_dwordx4 v[214:215], off
	s_add_i32 m0, s23, 0x16000
	v_lshl_add_u64 v[220:221], s[20:21], 0, v[158:159]
	global_load_lds_dwordx4 v[218:219], off
	s_mov_b32 m0, s55
	v_lshl_add_u64 v[222:223], s[20:21], 0, v[156:157]
	global_load_lds_dwordx4 v[220:221], off
	s_mov_b32 m0, s56
	s_nop 0
	global_load_lds_dwordx4 v[222:223], off
	s_waitcnt vmcnt(8)
	s_waitcnt lgkmcnt(0)
	s_barrier
	s_setprio 1
	v_mfma_f32_16x16x32_bf16 v[58:61], v[130:133], v[174:177], 0
	v_mfma_f32_16x16x32_bf16 v[54:57], v[138:141], v[174:177], 0
	v_mfma_f32_16x16x32_bf16 v[42:45], v[130:133], v[188:191], 0
	v_mfma_f32_16x16x32_bf16 v[38:41], v[138:141], v[188:191], 0
	v_mfma_f32_16x16x32_bf16 v[26:29], v[130:133], v[196:199], 0
	v_mfma_f32_16x16x32_bf16 v[22:25], v[138:141], v[196:199], 0
	v_mfma_f32_16x16x32_bf16 v[10:13], v[130:133], v[204:207], 0
	v_mfma_f32_16x16x32_bf16 v[6:9], v[138:141], v[204:207], 0
	v_mfma_f32_16x16x32_bf16 v[58:61], v[134:137], v[184:187], v[58:61]
	v_mfma_f32_16x16x32_bf16 v[54:57], v[142:145], v[184:187], v[54:57]
	v_mfma_f32_16x16x32_bf16 v[42:45], v[134:137], v[192:195], v[42:45]
	v_mfma_f32_16x16x32_bf16 v[38:41], v[142:145], v[192:195], v[38:41]
	v_mfma_f32_16x16x32_bf16 v[26:29], v[134:137], v[200:203], v[26:29]
	v_mfma_f32_16x16x32_bf16 v[22:25], v[142:145], v[200:203], v[22:25]
	v_mfma_f32_16x16x32_bf16 v[10:13], v[134:137], v[208:211], v[10:13]
	v_mfma_f32_16x16x32_bf16 v[6:9], v[142:145], v[208:211], v[6:9]
	v_mfma_f32_16x16x32_bf16 v[62:65], v[146:149], v[174:177], 0
	v_mfma_f32_16x16x32_bf16 v[50:53], v[166:169], v[174:177], 0
	v_mfma_f32_16x16x32_bf16 v[46:49], v[146:149], v[188:191], 0
	v_mfma_f32_16x16x32_bf16 v[34:37], v[166:169], v[188:191], 0
	v_mfma_f32_16x16x32_bf16 v[30:33], v[146:149], v[196:199], 0
	v_mfma_f32_16x16x32_bf16 v[18:21], v[166:169], v[196:199], 0
	v_mfma_f32_16x16x32_bf16 v[14:17], v[146:149], v[204:207], 0
	v_mfma_f32_16x16x32_bf16 v[2:5], v[166:169], v[204:207], 0
	v_mfma_f32_16x16x32_bf16 v[62:65], v[150:153], v[184:187], v[62:65]
	v_mfma_f32_16x16x32_bf16 v[50:53], v[170:173], v[184:187], v[50:53]
	v_mfma_f32_16x16x32_bf16 v[46:49], v[150:153], v[192:195], v[46:49]
	v_mfma_f32_16x16x32_bf16 v[34:37], v[170:173], v[192:195], v[34:37]
	v_mfma_f32_16x16x32_bf16 v[30:33], v[150:153], v[200:203], v[30:33]
	v_mfma_f32_16x16x32_bf16 v[18:21], v[170:173], v[200:203], v[18:21]
	v_mfma_f32_16x16x32_bf16 v[14:17], v[150:153], v[208:211], v[14:17]
	v_mfma_f32_16x16x32_bf16 v[2:5], v[170:173], v[208:211], v[2:5]
	s_setprio 0
	s_barrier
; #define PG8_STAGE(bufoff, gbase, voff) do { _Pragma("unroll") for (int _i = 0; _i < 2; ++_i) \
;         __builtin_amdgcn_global_load_lds((const unsigned*)((const char*)(gbase) + (voff)[_i]), (PG8_LAS unsigned*)(lds + (bufoff) + ldsw + _i * 8192), 16, 0, 0); } while (0)
; #define PG8_LDA(dst, b, h) do { _Pragma("unroll") for (int m = 0; m < 4; ++m) _Pragma("unroll") for (int k = 0; k < 2; ++k) dst[m][k] = *(const PG8_LAS bf16x8*)(lds + PG8_SA(b, h) + aoff + m * 2048 + k * 1024); } while (0)
; #define PG8_LDB(dst, b, h) do { _Pragma("unroll") for (int n = 0; n < 2; ++n) _Pragma("unroll") for (int k = 0; k < 2; ++k) dst[n][k] = *(const PG8_LAS bf16x8*)(lds + PG8_SB(b, h) + boff + n * 2048 + k * 1024); } while (0)
; #define PG8_MMA(ai, bj, At, Bt) do { __builtin_amdgcn_s_setprio(1); _Pragma("unroll") for (int m = 0; m < 4; ++m) _Pragma("unroll") for (int n = 0; n < 2; ++n) _Pragma("unroll") for (int k = 0; k < 2; ++k) \
;         acc[ai][bj][m][n] = __builtin_amdgcn_mfma_f32_16x16x32_bf16(Bt[n][k], At[m][k], acc[ai][bj][m][n], 0, 0, 0); __builtin_amdgcn_s_setprio(0); } while (0)
; #define PG8_WAIT_V(n) asm volatile("s_waitcnt vmcnt(" #n ")" ::: "memory")
; #define PG8_WAIT_L(n) asm volatile("s_waitcnt lgkmcnt(" #n ")" ::: "memory")
; #define PG8_BAR __builtin_amdgcn_s_barrier()
; #define PG8_SCHED __builtin_amdgcn_sched_barrier(0)
; template <class Epi, class Sched, bool ALIGN_EPI = false, bool SP2 = false>
; __device__ __forceinline__ void gemm_phase(PG8_LAS unsigned char* lds, const Gemm g, const Sched& S, const Epi& E) {
;     ...
;             PG8_LDB(B0, 1, 0); PG8_LDB(B1, 1, 1); PG8_SCHED; PG8_LDA(At, 1, 0); PG8_STAGE(PG8_SA(0, 1), a2 + hstep, voffA);
;             PG8_WAIT_V(8); PG8_WAIT_L(0); PG8_BAR; PG8_MMA(0, 0, At, B0); PG8_MMA(0, 1, At, B1); PG8_BAR; PG8_SCHED;
;             PG8_LDA(At, 1, 1); PG8_STAGE(PG8_SB(1, 0), b3, voffB); PG8_STAGE(PG8_SB(1, 1), b3 + hstep, voffB); PG8_STAGE(PG8_SA(1, 0), a3, voffA);
;             PG8_WAIT_V(8); PG8_WAIT_L(0); PG8_BAR; PG8_MMA(1, 0, At, B0); PG8_MMA(1, 1, At, B1); PG8_BAR; PG8_SCHED;
	ds_read_b128 v[130:133], v181 offset:32768
	ds_read_b128 v[134:137], v181 offset:33792
	ds_read_b128 v[138:141], v181 offset:34816
	ds_read_b128 v[142:145], v181 offset:35840
	ds_read_b128 v[146:149], v181 offset:49152
	ds_read_b128 v[150:153], v181 offset:50176
	ds_read_b128 v[166:169], v181 offset:51200
	ds_read_b128 v[170:173], v181 offset:52224
	s_mov_b32 m0, s57
	ds_read_b128 v[174:177], v183 offset:32768
	ds_read_b128 v[184:187], v183 offset:33792
	ds_read_b128 v[188:191], v183 offset:34816
	ds_read_b128 v[192:195], v183 offset:35840
	ds_read_b128 v[196:199], v183 offset:36864
	ds_read_b128 v[200:203], v183 offset:37888
	ds_read_b128 v[204:207], v183 offset:38912
	global_load_lds_dwordx4 v162, s[20:21]
	s_mov_b32 m0, s58
	ds_read_b128 v[208:211], v183 offset:39936
	global_load_lds_dwordx4 v164, s[20:21]
	s_waitcnt vmcnt(8)
	s_waitcnt lgkmcnt(0)
	s_barrier
	s_setprio 1
	v_mfma_f32_16x16x32_bf16 v[122:125], v[130:133], v[174:177], v[122:125]
	v_mfma_f32_16x16x32_bf16 v[118:121], v[138:141], v[174:177], v[118:121]
	v_mfma_f32_16x16x32_bf16 v[106:109], v[130:133], v[188:191], v[106:109]
	v_mfma_f32_16x16x32_bf16 v[102:105], v[138:141], v[188:191], v[102:105]
	v_mfma_f32_16x16x32_bf16 v[90:93], v[130:133], v[196:199], v[90:93]
	v_mfma_f32_16x16x32_bf16 v[86:89], v[138:141], v[196:199], v[86:89]
	v_mfma_f32_16x16x32_bf16 v[74:77], v[130:133], v[204:207], v[74:77]
	v_mfma_f32_16x16x32_bf16 v[70:73], v[138:141], v[204:207], v[70:73]
	v_mfma_f32_16x16x32_bf16 v[122:125], v[134:137], v[184:187], v[122:125]
	v_mfma_f32_16x16x32_bf16 v[118:121], v[142:145], v[184:187], v[118:121]
	v_mfma_f32_16x16x32_bf16 v[106:109], v[134:137], v[192:195], v[106:109]
	v_mfma_f32_16x16x32_bf16 v[102:105], v[142:145], v[192:195], v[102:105]
	v_mfma_f32_16x16x32_bf16 v[90:93], v[134:137], v[200:203], v[90:93]
	v_mfma_f32_16x16x32_bf16 v[86:89], v[142:145], v[200:203], v[86:89]
	v_mfma_f32_16x16x32_bf16 v[74:77], v[134:137], v[208:211], v[74:77]
	v_mfma_f32_16x16x32_bf16 v[70:73], v[142:145], v[208:211], v[70:73]
	v_mfma_f32_16x16x32_bf16 v[126:129], v[146:149], v[174:177], v[126:129]
	v_mfma_f32_16x16x32_bf16 v[114:117], v[166:169], v[174:177], v[114:117]
	v_mfma_f32_16x16x32_bf16 v[110:113], v[146:149], v[188:191], v[110:113]
	v_mfma_f32_16x16x32_bf16 v[98:101], v[166:169], v[188:191], v[98:101]
	v_mfma_f32_16x16x32_bf16 v[94:97], v[146:149], v[196:199], v[94:97]
	v_mfma_f32_16x16x32_bf16 v[82:85], v[166:169], v[196:199], v[82:85]
	v_mfma_f32_16x16x32_bf16 v[78:81], v[146:149], v[204:207], v[78:81]
	v_mfma_f32_16x16x32_bf16 v[66:69], v[166:169], v[204:207], v[66:69]
	v_mfma_f32_16x16x32_bf16 v[126:129], v[150:153], v[184:187], v[126:129]
	v_mfma_f32_16x16x32_bf16 v[114:117], v[170:173], v[184:187], v[114:117]
	v_mfma_f32_16x16x32_bf16 v[110:113], v[150:153], v[192:195], v[110:113]
	v_mfma_f32_16x16x32_bf16 v[98:101], v[170:173], v[192:195], v[98:101]
	v_mfma_f32_16x16x32_bf16 v[94:97], v[150:153], v[200:203], v[94:97]
	v_mfma_f32_16x16x32_bf16 v[82:85], v[170:173], v[200:203], v[82:85]
	v_mfma_f32_16x16x32_bf16 v[78:81], v[150:153], v[208:211], v[78:81]
	v_mfma_f32_16x16x32_bf16 v[66:69], v[170:173], v[208:211], v[66:69]
	s_setprio 0
	s_barrier
	s_add_i32 m0, s23, 0x17f80
	ds_read_b128 v[174:177], v183 offset:49152
	ds_read_b128 v[184:187], v183 offset:50176
	ds_read_b128 v[188:191], v183 offset:51200
	global_load_lds_dwordx4 v[178:179], off offset:128
	s_add_i32 m0, s23, 0x19f80
	ds_read_b128 v[192:195], v183 offset:52224
	global_load_lds_dwordx4 v[212:213], off offset:128
	s_add_i32 m0, s23, 0x1bf80
	ds_read_b128 v[196:199], v183 offset:53248
	global_load_lds_dwordx4 v[214:215], off offset:128
	s_add_i32 m0, s23, 0x1df80
	ds_read_b128 v[200:203], v183 offset:54272
	global_load_lds_dwordx4 v[218:219], off offset:128
	s_sub_i32 m0, s59, 0x80
	ds_read_b128 v[204:207], v183 offset:55296
	global_load_lds_dwordx4 v[220:221], off offset:128
	s_sub_i32 m0, s60, 0x80
	ds_read_b128 v[208:211], v183 offset:56320
	global_load_lds_dwordx4 v[222:223], off offset:128
	s_waitcnt vmcnt(8)
	s_waitcnt lgkmcnt(0)
	s_barrier
	s_setprio 1
	v_mfma_f32_16x16x32_bf16 v[58:61], v[130:133], v[174:177], v[58:61]
	v_mfma_f32_16x16x32_bf16 v[54:57], v[138:141], v[174:177], v[54:57]
	v_mfma_f32_16x16x32_bf16 v[42:45], v[130:133], v[188:191], v[42:45]
	v_mfma_f32_16x16x32_bf16 v[38:41], v[138:141], v[188:191], v[38:41]
	v_mfma_f32_16x16x32_bf16 v[26:29], v[130:133], v[196:199], v[26:29]
	v_mfma_f32_16x16x32_bf16 v[22:25], v[138:141], v[196:199], v[22:25]
	v_mfma_f32_16x16x32_bf16 v[10:13], v[130:133], v[204:207], v[10:13]
	v_mfma_f32_16x16x32_bf16 v[6:9], v[138:141], v[204:207], v[6:9]
	v_mfma_f32_16x16x32_bf16 v[58:61], v[134:137], v[184:187], v[58:61]
	v_mfma_f32_16x16x32_bf16 v[54:57], v[142:145], v[184:187], v[54:57]
	v_mfma_f32_16x16x32_bf16 v[42:45], v[134:137], v[192:195], v[42:45]
	v_mfma_f32_16x16x32_bf16 v[38:41], v[142:145], v[192:195], v[38:41]
	v_mfma_f32_16x16x32_bf16 v[26:29], v[134:137], v[200:203], v[26:29]
	v_mfma_f32_16x16x32_bf16 v[22:25], v[142:145], v[200:203], v[22:25]
	v_mfma_f32_16x16x32_bf16 v[10:13], v[134:137], v[208:211], v[10:13]
	v_mfma_f32_16x16x32_bf16 v[6:9], v[142:145], v[208:211], v[6:9]
	v_mfma_f32_16x16x32_bf16 v[62:65], v[146:149], v[174:177], v[62:65]
	v_mfma_f32_16x16x32_bf16 v[50:53], v[166:169], v[174:177], v[50:53]
	v_mfma_f32_16x16x32_bf16 v[46:49], v[146:149], v[188:191], v[46:49]
	v_mfma_f32_16x16x32_bf16 v[34:37], v[166:169], v[188:191], v[34:37]
	v_mfma_f32_16x16x32_bf16 v[30:33], v[146:149], v[196:199], v[30:33]
	v_mfma_f32_16x16x32_bf16 v[18:21], v[166:169], v[196:199], v[18:21]
	v_mfma_f32_16x16x32_bf16 v[14:17], v[146:149], v[204:207], v[14:17]
	v_mfma_f32_16x16x32_bf16 v[2:5], v[166:169], v[204:207], v[2:5]
	v_mfma_f32_16x16x32_bf16 v[62:65], v[150:153], v[184:187], v[62:65]
	v_mfma_f32_16x16x32_bf16 v[50:53], v[170:173], v[184:187], v[50:53]
	v_mfma_f32_16x16x32_bf16 v[46:49], v[150:153], v[192:195], v[46:49]
	v_mfma_f32_16x16x32_bf16 v[34:37], v[170:173], v[192:195], v[34:37]
	v_mfma_f32_16x16x32_bf16 v[30:33], v[150:153], v[200:203], v[30:33]
	v_mfma_f32_16x16x32_bf16 v[18:21], v[170:173], v[200:203], v[18:21]
	v_mfma_f32_16x16x32_bf16 v[14:17], v[150:153], v[208:211], v[14:17]
	v_mfma_f32_16x16x32_bf16 v[2:5], v[170:173], v[208:211], v[2:5]
	s_setprio 0
	s_barrier
	s_add_u32 s8, s8, 0x100
	s_addc_u32 s9, s9, 0
	s_add_u32 s52, s52, 0x100
	s_addc_u32 s53, s53, 0
	s_cmp_ge_i32 s68, s62
	s_mov_b32 s20, s68
	s_cbranch_scc1 .Lpz_exit_641
